# attention loops: V key tiles loaded HBM->LDS directly (global_load_lds_dwordx4) instead of VGPR staging + ds_write
# speedup vs baseline: 1.0224x; 1.0224x over previous
.LBB0_654:
	v_lshlrev_b32_e32 v16, 3, v18
	v_lshrrev_b32_e32 v14, 2, v19
	v_lshlrev_b32_e32 v15, 1, v18
	v_and_b32_e32 v16, 24, v16
	v_and_or_b32 v15, v15, 32, v16
	v_and_or_b32 v14, v14, 3, v156
	v_lshl_or_b32 v14, v14, 6, v15
	v_lshl_add_u64 v[136:137], v[12:13], 1, s[12:13]
	s_add_i32 s12, s10, 2
	v_mul_u32_u24_e32 v164, 0x90, v20
	v_lshl_add_u64 v[138:139], v[144:145], 1, s[14:15]
	s_cmp_ge_i32 s12, s35
	v_add_u32_e32 v158, 0, v30
	v_add_u32_e32 v159, 0, v14
	s_barrier
	v_readfirstlane_b32 s54, v155
	s_add_i32 s55, s54, 0x8800
	s_add_i32 s54, s54, 0x6800
	v_add_u32_e32 v218, v164, v30
	s_and_b32 s12, s33, 1
	s_lshl_b32 s12, s12, 5
	v_lshlrev_b32_e32 v219, 2, v21
	v_sub_u32_e32 v219, v20, v219
	v_add_u32_e32 v219, s12, v219
	s_lshr_b32 s11, s33, 1
	v_mov_b32_e32 v14, 0
	v_mov_b32_e32 v15, 0
	v_mov_b32_e32 v16, 0
	v_mov_b32_e32 v17, 0
	v_mov_b32_e32 v18, 0
	v_mov_b32_e32 v19, 0
	v_mov_b32_e32 v20, 0
	v_mov_b32_e32 v21, 0
	v_mov_b32_e32 v22, 0
	v_mov_b32_e32 v23, 0
	v_mov_b32_e32 v24, 0
	v_mov_b32_e32 v25, 0
	v_mov_b32_e32 v26, 0
	v_mov_b32_e32 v27, 0
	v_mov_b32_e32 v28, 0
	v_mov_b32_e32 v29, 0
	v_mov_b32_e32 v30, 0
	v_mov_b32_e32 v31, 0
	v_mov_b32_e32 v32, 0
	v_mov_b32_e32 v33, 0
	v_mov_b32_e32 v34, 0
	v_mov_b32_e32 v35, 0
	v_mov_b32_e32 v36, 0
	v_mov_b32_e32 v37, 0
	v_mov_b32_e32 v38, 0
	v_mov_b32_e32 v39, 0
	v_mov_b32_e32 v40, 0
	v_mov_b32_e32 v41, 0
	v_mov_b32_e32 v42, 0
	v_mov_b32_e32 v43, 0
	v_mov_b32_e32 v44, 0
	v_mov_b32_e32 v45, 0
	v_mov_b32_e32 v161, 0
	v_mov_b32_e32 v160, 0xf149f2ca
	s_add_i32 s12, s10, 2
	s_ashr_i32 s13, s12, 31
	s_lshl_b64 s[14:15], s[12:13], 16
	v_lshl_add_u64 v[244:245], v[136:137], 0, s[14:15]
	s_lshl_b64 s[14:15], s[12:13], 8
	v_mov_b32_e32 v141, 0
	v_lshl_add_u64 v[250:251], s[4:5], 0, v[140:141]
	v_lshl_add_u64 v[250:251], v[250:251], 0, s[14:15]
	s_add_i32 s12, s10, 1
	s_ashr_i32 s13, s12, 31
	s_lshl_b64 s[14:15], s[12:13], 16
	v_lshl_add_u64 v[248:249], v[138:139], 0, s[14:15]
	global_load_dwordx4 v[114:117], v[244:245], off
	s_and_saveexec_b64 s[12:13], s[6:7]
	s_cbranch_execz .Lf3_nockp
	global_load_dword v152, v[250:251], off
.Lf3_nockp:
	s_or_b64 exec, exec, s[12:13]
	s_mov_b32 m0, s55
	s_nop 0
	global_load_lds_dwordx4 v[248:249], off
	s_mov_b64 s[14:15], 0x10000
	v_lshl_add_u64 v[242:243], v[244:245], 0, s[14:15]
	v_lshl_add_u64 v[244:245], v[242:243], 0, s[14:15]
	v_lshl_add_u64 v[246:247], v[248:249], 0, s[14:15]
	v_lshl_add_u64 v[248:249], v[246:247], 0, s[14:15]
	s_mov_b64 s[14:15], 0x100
	v_lshl_add_u64 v[250:251], v[250:251], 0, s[14:15]
	ds_read_b128 v[78:81], v158 offset:43264
	ds_read_b128 v[82:85], v158 offset:43296
	ds_read_b128 v[86:89], v158 offset:43328
	ds_read_b128 v[90:93], v158 offset:43360
	ds_read_b128 v[94:97], v158 offset:43392
	ds_read_b128 v[98:101], v158 offset:43424
	ds_read_b128 v[102:105], v158 offset:43456
	ds_read_b128 v[106:109], v158 offset:43488
	s_waitcnt lgkmcnt(4)
	ds_read_b128 v[190:193], v218 offset:13312
	ds_read_b128 v[194:197], v218 offset:17920
	ds_read_b128 v[198:201], v218 offset:13344
	ds_read_b128 v[202:205], v218 offset:17952
	ds_read_b128 v[206:209], v218 offset:13376
	ds_read_b128 v[210:213], v218 offset:17984
	ds_read_b128 v[214:217], v218 offset:13408
	ds_read_b128 v[222:225], v218 offset:18016
	v_max3_f32 v124, v46, v47, v48
	v_max3_f32 v125, v49, v50, v51
	v_max3_f32 v124, v124, v52, v53
	v_max3_f32 v125, v125, v54, v55
	v_max3_f32 v124, v124, v56, v57
	v_max3_f32 v125, v125, v58, v59
	v_max3_f32 v124, v124, v60, v61
	v_max3_f32 v125, v125, v62, v63
	v_max3_f32 v124, v124, v64, v65
	v_max3_f32 v125, v125, v66, v67
	v_max3_f32 v124, v124, v68, v69
	v_max3_f32 v125, v125, v70, v71
	v_max3_f32 v124, v124, v72, v73
	v_max3_f32 v125, v125, v74, v75
	v_max3_f32 v124, v124, v76, v77
	v_max_f32_e32 v124, v124, v125
	v_mov_b32_e32 v125, v124
	s_nop 1
	v_permlane32_swap_b32_e32 v124, v125
	v_max_f32_e32 v126, v124, v125
	s_add_i32 s12, s10, 6
	s_cmp_lt_i32 s12, s41
	s_cbranch_scc1 .Lf3_loop
	s_add_i32 s12, s10, 4
	s_cmp_lt_i32 s12, s41
	s_cbranch_scc1 .Lf3_tail0
	s_branch .Lf3_tail2

.Lf3_nocwa:
	s_or_b64 exec, exec, s[12:13]
	v_exp_f32_e32 v70, v70
	v_exp_f32_e32 v71, v71
	v_exp_f32_e32 v72, v72
	v_exp_f32_e32 v73, v73
	v_exp_f32_e32 v74, v74
	v_exp_f32_e32 v75, v75
	v_exp_f32_e32 v76, v76
	v_exp_f32_e32 v77, v77
	v_add_f32_e32 v122, v122, v70
	v_add_f32_e32 v123, v123, v71
	v_add_f32_e32 v122, v122, v72
	v_add_f32_e32 v123, v123, v73
	v_add_f32_e32 v122, v122, v74
	v_add_f32_e32 v123, v123, v75
	v_add_f32_e32 v122, v122, v76
	v_add_f32_e32 v123, v123, v77
	v_cvt_pk_bf16_f32 v238, v70, v71
	v_cvt_pk_bf16_f32 v239, v72, v73
	v_cvt_pk_bf16_f32 v240, v74, v75
	v_cvt_pk_bf16_f32 v241, v76, v77
	v_add_f32_e32 v122, v122, v123
	v_add_f32_e32 v161, v161, v122
	s_waitcnt lgkmcnt(0)
	s_barrier
	ds_read_b128 v[46:49], v158 offset:43008
	ds_read_b128 v[50:53], v158 offset:43040
	ds_read_b128 v[54:57], v158 offset:43072
	ds_read_b128 v[58:61], v158 offset:43104
	ds_read_b128 v[62:65], v158 offset:43136
	ds_read_b128 v[66:69], v158 offset:43168
	ds_read_b128 v[70:73], v158 offset:43200
	ds_read_b128 v[74:77], v158 offset:43232
	v_mfma_f32_32x32x16_bf16 v[14:29], v[190:193], v[226:229], v[14:29]
	ds_read_b128 v[190:193], v218
	v_max3_f32 v124, v78, v79, v80
	v_max3_f32 v125, v81, v82, v83
	v_max3_f32 v124, v124, v84, v85
	v_mfma_f32_32x32x16_bf16 v[30:45], v[194:197], v[226:229], v[30:45]
	ds_read_b128 v[194:197], v218 offset:4608
	global_load_dwordx4 v[114:117], v[242:243], off
	s_and_saveexec_b64 s[12:13], s[6:7]
	s_cbranch_execz .Lf3_nocka
	global_load_dword v152, v[250:251], off
.Lf3_nocka:
	s_or_b64 exec, exec, s[12:13]
	s_mov_b32 m0, s54
	s_nop 0
	global_load_lds_dwordx4 v[246:247], off
	v_max3_f32 v125, v125, v86, v87
	v_max3_f32 v124, v124, v88, v89
	v_max3_f32 v125, v125, v90, v91
	v_mfma_f32_32x32x16_bf16 v[14:29], v[198:201], v[230:233], v[14:29]
	ds_read_b128 v[198:201], v218 offset:32
	v_max3_f32 v124, v124, v92, v93
	v_max3_f32 v125, v125, v94, v95
	v_max3_f32 v124, v124, v96, v97
	v_mfma_f32_32x32x16_bf16 v[30:45], v[202:205], v[230:233], v[30:45]
	ds_read_b128 v[202:205], v218 offset:4640
	v_max3_f32 v125, v125, v98, v99
	v_max3_f32 v124, v124, v100, v101
	v_max3_f32 v125, v125, v102, v103
	v_mfma_f32_32x32x16_bf16 v[14:29], v[206:209], v[234:237], v[14:29]
	ds_read_b128 v[206:209], v218 offset:64
	v_max3_f32 v124, v124, v104, v105
	v_max3_f32 v125, v125, v106, v107
	v_mfma_f32_32x32x16_bf16 v[30:45], v[210:213], v[234:237], v[30:45]
	ds_read_b128 v[210:213], v218 offset:4672
	v_max3_f32 v124, v124, v108, v109
	v_max_f32_e32 v124, v124, v125
	v_mfma_f32_32x32x16_bf16 v[14:29], v[214:217], v[238:241], v[14:29]
	ds_read_b128 v[214:217], v218 offset:96
	v_mov_b32_e32 v125, v124
	s_nop 1
	v_mfma_f32_32x32x16_bf16 v[30:45], v[222:225], v[238:241], v[30:45]
	s_waitcnt lgkmcnt(14)
	ds_read_b128 v[222:225], v218 offset:4704
	v_permlane32_swap_b32_e32 v124, v125
	v_max_f32_e32 v126, v124, v125
	v_lshl_add_u64 v[242:243], v[242:243], 0, s[46:47]
	v_lshl_add_u64 v[246:247], v[246:247], 0, s[46:47]
	v_add_f32_e32 v127, 0x41800000, v160
	v_cmp_gt_f32_e32 vcc, v126, v127
	s_cbranch_vccnz .Lf3_rescb

.Lf3_nocwb:
	s_or_b64 exec, exec, s[12:13]
	v_exp_f32_e32 v102, v102
	v_exp_f32_e32 v103, v103
	v_exp_f32_e32 v104, v104
	v_exp_f32_e32 v105, v105
	v_exp_f32_e32 v106, v106
	v_exp_f32_e32 v107, v107
	v_exp_f32_e32 v108, v108
	v_exp_f32_e32 v109, v109
	v_add_f32_e32 v122, v122, v102
	v_add_f32_e32 v123, v123, v103
	v_add_f32_e32 v122, v122, v104
	v_add_f32_e32 v123, v123, v105
	v_add_f32_e32 v122, v122, v106
	v_add_f32_e32 v123, v123, v107
	v_add_f32_e32 v122, v122, v108
	v_add_f32_e32 v123, v123, v109
	v_cvt_pk_bf16_f32 v238, v102, v103
	v_cvt_pk_bf16_f32 v239, v104, v105
	v_cvt_pk_bf16_f32 v240, v106, v107
	v_cvt_pk_bf16_f32 v241, v108, v109
	v_add_f32_e32 v122, v122, v123
	v_add_f32_e32 v161, v161, v122
	s_waitcnt lgkmcnt(0)
	s_barrier
	ds_read_b128 v[78:81], v158 offset:43264
	ds_read_b128 v[82:85], v158 offset:43296
	ds_read_b128 v[86:89], v158 offset:43328
	ds_read_b128 v[90:93], v158 offset:43360
	ds_read_b128 v[94:97], v158 offset:43392
	ds_read_b128 v[98:101], v158 offset:43424
	ds_read_b128 v[102:105], v158 offset:43456
	ds_read_b128 v[106:109], v158 offset:43488
	v_mfma_f32_32x32x16_bf16 v[14:29], v[190:193], v[226:229], v[14:29]
	ds_read_b128 v[190:193], v218 offset:13312
	v_max3_f32 v124, v46, v47, v48
	v_max3_f32 v125, v49, v50, v51
	v_max3_f32 v124, v124, v52, v53
	v_mfma_f32_32x32x16_bf16 v[30:45], v[194:197], v[226:229], v[30:45]
	ds_read_b128 v[194:197], v218 offset:17920
	global_load_dwordx4 v[114:117], v[244:245], off
	s_and_saveexec_b64 s[12:13], s[6:7]
	s_cbranch_execz .Lf3_nockb
	global_load_dword v152, v[250:251], off offset:256
.Lf3_nockb:
	s_or_b64 exec, exec, s[12:13]
	s_mov_b32 m0, s55
	s_nop 0
	global_load_lds_dwordx4 v[248:249], off
	v_max3_f32 v125, v125, v54, v55
	v_max3_f32 v124, v124, v56, v57
	v_max3_f32 v125, v125, v58, v59
	v_mfma_f32_32x32x16_bf16 v[14:29], v[198:201], v[230:233], v[14:29]
	ds_read_b128 v[198:201], v218 offset:13344
	v_max3_f32 v124, v124, v60, v61
	v_max3_f32 v125, v125, v62, v63
	v_max3_f32 v124, v124, v64, v65
	v_mfma_f32_32x32x16_bf16 v[30:45], v[202:205], v[230:233], v[30:45]
	ds_read_b128 v[202:205], v218 offset:17952
	v_max3_f32 v125, v125, v66, v67
	v_max3_f32 v124, v124, v68, v69
	v_max3_f32 v125, v125, v70, v71
	v_mfma_f32_32x32x16_bf16 v[14:29], v[206:209], v[234:237], v[14:29]
	ds_read_b128 v[206:209], v218 offset:13376
	v_max3_f32 v124, v124, v72, v73
	v_max3_f32 v125, v125, v74, v75
	v_mfma_f32_32x32x16_bf16 v[30:45], v[210:213], v[234:237], v[30:45]
	ds_read_b128 v[210:213], v218 offset:17984
	v_max3_f32 v124, v124, v76, v77
	v_max_f32_e32 v124, v124, v125
	v_mfma_f32_32x32x16_bf16 v[14:29], v[214:217], v[238:241], v[14:29]
	ds_read_b128 v[214:217], v218 offset:13408
	v_mov_b32_e32 v125, v124
	s_nop 1
	v_mfma_f32_32x32x16_bf16 v[30:45], v[222:225], v[238:241], v[30:45]
	s_waitcnt lgkmcnt(14)
	ds_read_b128 v[222:225], v218 offset:18016
	v_permlane32_swap_b32_e32 v124, v125
	v_max_f32_e32 v126, v124, v125
	v_lshl_add_u64 v[244:245], v[244:245], 0, s[46:47]
	v_lshl_add_u64 v[248:249], v[248:249], 0, s[46:47]
	v_lshl_add_u64 v[250:251], v[250:251], 0, s[48:49]
	s_add_i32 s10, s10, 2
	s_add_i32 s12, s10, 6
	s_cmp_lt_i32 s12, s41
	s_cbranch_scc1 .Lf3_loop

.Lf3_nockt0FULL:
	s_or_b64 exec, exec, s[12:13]
	s_mov_b32 m0, s54
	s_nop 0
	global_load_lds_dwordx4 v[246:247], off
	v_max3_f32 v125, v125, v86, v87
	v_max3_f32 v124, v124, v88, v89
	v_max3_f32 v125, v125, v90, v91
	v_mfma_f32_32x32x16_bf16 v[14:29], v[198:201], v[230:233], v[14:29]
	ds_read_b128 v[198:201], v218 offset:32
	v_max3_f32 v124, v124, v92, v93
	v_max3_f32 v125, v125, v94, v95
	v_max3_f32 v124, v124, v96, v97
	v_mfma_f32_32x32x16_bf16 v[30:45], v[202:205], v[230:233], v[30:45]
	ds_read_b128 v[202:205], v218 offset:4640
	v_max3_f32 v125, v125, v98, v99
	v_max3_f32 v124, v124, v100, v101
	v_max3_f32 v125, v125, v102, v103
	v_mfma_f32_32x32x16_bf16 v[14:29], v[206:209], v[234:237], v[14:29]
	ds_read_b128 v[206:209], v218 offset:64
	v_max3_f32 v124, v124, v104, v105
	v_max3_f32 v125, v125, v106, v107
	v_mfma_f32_32x32x16_bf16 v[30:45], v[210:213], v[234:237], v[30:45]
	ds_read_b128 v[210:213], v218 offset:4672
	v_max3_f32 v124, v124, v108, v109
	v_max_f32_e32 v124, v124, v125
	v_mfma_f32_32x32x16_bf16 v[14:29], v[214:217], v[238:241], v[14:29]
	ds_read_b128 v[214:217], v218 offset:96
	v_mov_b32_e32 v125, v124
	s_nop 1
	v_mfma_f32_32x32x16_bf16 v[30:45], v[222:225], v[238:241], v[30:45]
	s_waitcnt lgkmcnt(14)
	ds_read_b128 v[222:225], v218 offset:4704
	v_permlane32_swap_b32_e32 v124, v125
	v_max_f32_e32 v126, v124, v125
	v_lshl_add_u64 v[242:243], v[242:243], 0, s[46:47]
	v_lshl_add_u64 v[246:247], v[246:247], 0, s[46:47]

.Lf3_nocwt1FULLM:
	s_or_b64 exec, exec, s[12:13]
	v_exp_f32_e32 v102, v102
	v_exp_f32_e32 v103, v103
	v_exp_f32_e32 v104, v104
	v_exp_f32_e32 v105, v105
	v_exp_f32_e32 v106, v106
	v_exp_f32_e32 v107, v107
	v_exp_f32_e32 v108, v108
	v_exp_f32_e32 v109, v109
	v_add_f32_e32 v122, v122, v102
	v_add_f32_e32 v123, v123, v103
	v_add_f32_e32 v122, v122, v104
	v_add_f32_e32 v123, v123, v105
	v_add_f32_e32 v122, v122, v106
	v_add_f32_e32 v123, v123, v107
	v_add_f32_e32 v122, v122, v108
	v_add_f32_e32 v123, v123, v109
	v_cvt_pk_bf16_f32 v238, v102, v103
	v_cvt_pk_bf16_f32 v239, v104, v105
	v_cvt_pk_bf16_f32 v240, v106, v107
	v_cvt_pk_bf16_f32 v241, v108, v109
	v_add_f32_e32 v122, v122, v123
	v_add_f32_e32 v161, v161, v122
	s_waitcnt lgkmcnt(0)
	s_barrier
	ds_read_b128 v[78:81], v158 offset:43264
	ds_read_b128 v[82:85], v158 offset:43296
	ds_read_b128 v[86:89], v158 offset:43328
	ds_read_b128 v[90:93], v158 offset:43360
	ds_read_b128 v[94:97], v158 offset:43392
	ds_read_b128 v[98:101], v158 offset:43424
	ds_read_b128 v[102:105], v158 offset:43456
	ds_read_b128 v[106:109], v158 offset:43488
	v_mfma_f32_32x32x16_bf16 v[14:29], v[190:193], v[226:229], v[14:29]
	ds_read_b128 v[190:193], v218 offset:13312
	v_cmp_le_i32_e64 s[52:53], 0, v219
	v_cmp_le_i32_e64 s[14:15], 32, v219
	v_cmp_le_i32_e64 s[16:17], 1, v219
	v_cndmask_b32_e64 v46, v220, v46, s[52:53]
	v_cmp_le_i32_e64 s[52:53], 33, v219
	v_cndmask_b32_e64 v62, v220, v62, s[14:15]
	v_cmp_le_i32_e64 s[14:15], 2, v219
	v_cndmask_b32_e64 v47, v220, v47, s[16:17]
	v_cmp_le_i32_e64 s[16:17], 34, v219
	v_cndmask_b32_e64 v63, v220, v63, s[52:53]
	v_cmp_le_i32_e64 s[52:53], 3, v219
	v_mfma_f32_32x32x16_bf16 v[30:45], v[194:197], v[226:229], v[30:45]
	ds_read_b128 v[194:197], v218 offset:17920
	global_load_dwordx4 v[114:117], v[244:245], off
	s_and_saveexec_b64 s[12:13], s[6:7]
	s_cbranch_execz .Lf3_nockt1FULLM
	global_load_dword v152, v[250:251], off offset:256
.Lf3_nockt1FULLM:
	s_or_b64 exec, exec, s[12:13]
	s_mov_b32 m0, s55
	s_nop 0
	global_load_lds_dwordx4 v[248:249], off
	v_cndmask_b32_e64 v48, v220, v48, s[14:15]
	v_cmp_le_i32_e64 s[14:15], 35, v219
	v_cndmask_b32_e64 v64, v220, v64, s[16:17]
	v_cmp_le_i32_e64 s[16:17], 8, v219
	v_cndmask_b32_e64 v49, v220, v49, s[52:53]
	v_cmp_le_i32_e64 s[52:53], 40, v219
	v_cndmask_b32_e64 v65, v220, v65, s[14:15]
	v_cmp_le_i32_e64 s[14:15], 9, v219
	v_cndmask_b32_e64 v50, v220, v50, s[16:17]
	v_cmp_le_i32_e64 s[16:17], 41, v219
	v_cndmask_b32_e64 v66, v220, v66, s[52:53]
	v_mfma_f32_32x32x16_bf16 v[14:29], v[198:201], v[230:233], v[14:29]
	ds_read_b128 v[198:201], v218 offset:13344
	v_cmp_le_i32_e64 s[52:53], 10, v219
	v_cndmask_b32_e64 v51, v220, v51, s[14:15]
	v_cmp_le_i32_e64 s[14:15], 42, v219
	v_cndmask_b32_e64 v67, v220, v67, s[16:17]
	v_cmp_le_i32_e64 s[16:17], 11, v219
	v_cndmask_b32_e64 v52, v220, v52, s[52:53]
	v_cmp_le_i32_e64 s[52:53], 43, v219
	v_cndmask_b32_e64 v68, v220, v68, s[14:15]
	v_cmp_le_i32_e64 s[14:15], 16, v219
	v_cndmask_b32_e64 v53, v220, v53, s[16:17]
	v_cmp_le_i32_e64 s[16:17], 48, v219
	v_mfma_f32_32x32x16_bf16 v[30:45], v[202:205], v[230:233], v[30:45]
	ds_read_b128 v[202:205], v218 offset:17952
	v_cndmask_b32_e64 v69, v220, v69, s[52:53]
	v_cmp_le_i32_e64 s[52:53], 17, v219
	v_cndmask_b32_e64 v54, v220, v54, s[14:15]
	v_cmp_le_i32_e64 s[14:15], 49, v219
	v_cndmask_b32_e64 v70, v220, v70, s[16:17]
	v_cmp_le_i32_e64 s[16:17], 18, v219
	v_cndmask_b32_e64 v55, v220, v55, s[52:53]
	v_cmp_le_i32_e64 s[52:53], 50, v219
	v_cndmask_b32_e64 v71, v220, v71, s[14:15]
	v_cmp_le_i32_e64 s[14:15], 19, v219
	v_cndmask_b32_e64 v56, v220, v56, s[16:17]
	v_mfma_f32_32x32x16_bf16 v[14:29], v[206:209], v[234:237], v[14:29]
	ds_read_b128 v[206:209], v218 offset:13376
	v_cmp_le_i32_e64 s[16:17], 51, v219
	v_cndmask_b32_e64 v72, v220, v72, s[52:53]
	v_cmp_le_i32_e64 s[52:53], 24, v219
	v_cndmask_b32_e64 v57, v220, v57, s[14:15]
	v_cmp_le_i32_e64 s[14:15], 56, v219
	v_cndmask_b32_e64 v73, v220, v73, s[16:17]
	v_cmp_le_i32_e64 s[16:17], 25, v219
	v_cndmask_b32_e64 v58, v220, v58, s[52:53]
	v_cmp_le_i32_e64 s[52:53], 57, v219
	v_cndmask_b32_e64 v74, v220, v74, s[14:15]
	v_mfma_f32_32x32x16_bf16 v[30:45], v[210:213], v[234:237], v[30:45]
	ds_read_b128 v[210:213], v218 offset:17984
	v_cmp_le_i32_e64 s[14:15], 26, v219
	v_cndmask_b32_e64 v59, v220, v59, s[16:17]
	v_cmp_le_i32_e64 s[16:17], 58, v219
	v_cndmask_b32_e64 v75, v220, v75, s[52:53]
	v_cmp_le_i32_e64 s[52:53], 27, v219
	v_cndmask_b32_e64 v60, v220, v60, s[14:15]
	v_cmp_le_i32_e64 s[14:15], 59, v219
	v_cndmask_b32_e64 v76, v220, v76, s[16:17]
	v_cndmask_b32_e64 v61, v220, v61, s[52:53]
	v_cndmask_b32_e64 v77, v220, v77, s[14:15]
	v_mfma_f32_32x32x16_bf16 v[14:29], v[214:217], v[238:241], v[14:29]
	ds_read_b128 v[214:217], v218 offset:13408
	v_max3_f32 v124, v46, v47, v48
	v_max3_f32 v125, v49, v50, v51
	v_max3_f32 v124, v124, v52, v53
	v_max3_f32 v125, v125, v54, v55
	v_max3_f32 v124, v124, v56, v57
	v_max3_f32 v125, v125, v58, v59
	v_max3_f32 v124, v124, v60, v61
	v_max3_f32 v125, v125, v62, v63
	v_max3_f32 v124, v124, v64, v65
	v_max3_f32 v125, v125, v66, v67
	v_mfma_f32_32x32x16_bf16 v[30:45], v[222:225], v[238:241], v[30:45]
	s_waitcnt lgkmcnt(14)
	ds_read_b128 v[222:225], v218 offset:18016
	v_max3_f32 v124, v124, v68, v69
	v_max3_f32 v125, v125, v70, v71
	v_max3_f32 v124, v124, v72, v73
	v_max3_f32 v125, v125, v74, v75
	v_max3_f32 v124, v124, v76, v77
	v_max_f32_e32 v124, v124, v125
	v_mov_b32_e32 v125, v124
	s_nop 1
	v_permlane32_swap_b32_e32 v124, v125
	v_max_f32_e32 v126, v124, v125
	v_lshl_add_u64 v[244:245], v[244:245], 0, s[46:47]
	v_lshl_add_u64 v[248:249], v[248:249], 0, s[46:47]
	v_lshl_add_u64 v[250:251], v[250:251], 0, s[48:49]
	s_branch .Lf3_tail2

.Lf3_nockt1FULL:
	s_or_b64 exec, exec, s[12:13]
	s_mov_b32 m0, s55
	s_nop 0
	global_load_lds_dwordx4 v[248:249], off
	v_max3_f32 v125, v125, v54, v55
	v_max3_f32 v124, v124, v56, v57
	v_max3_f32 v125, v125, v58, v59
	v_mfma_f32_32x32x16_bf16 v[14:29], v[198:201], v[230:233], v[14:29]
	ds_read_b128 v[198:201], v218 offset:13344
	v_max3_f32 v124, v124, v60, v61
	v_max3_f32 v125, v125, v62, v63
	v_max3_f32 v124, v124, v64, v65
	v_mfma_f32_32x32x16_bf16 v[30:45], v[202:205], v[230:233], v[30:45]
	ds_read_b128 v[202:205], v218 offset:17952
	v_max3_f32 v125, v125, v66, v67
	v_max3_f32 v124, v124, v68, v69
	v_max3_f32 v125, v125, v70, v71
	v_mfma_f32_32x32x16_bf16 v[14:29], v[206:209], v[234:237], v[14:29]
	ds_read_b128 v[206:209], v218 offset:13376
	v_max3_f32 v124, v124, v72, v73
	v_max3_f32 v125, v125, v74, v75
	v_mfma_f32_32x32x16_bf16 v[30:45], v[210:213], v[234:237], v[30:45]
	ds_read_b128 v[210:213], v218 offset:17984
	v_max3_f32 v124, v124, v76, v77
	v_max_f32_e32 v124, v124, v125
	v_mfma_f32_32x32x16_bf16 v[14:29], v[214:217], v[238:241], v[14:29]
	ds_read_b128 v[214:217], v218 offset:13408
	v_mov_b32_e32 v125, v124
	s_nop 1
	v_mfma_f32_32x32x16_bf16 v[30:45], v[222:225], v[238:241], v[30:45]
	s_waitcnt lgkmcnt(14)
	ds_read_b128 v[222:225], v218 offset:18016
	v_permlane32_swap_b32_e32 v124, v125
	v_max_f32_e32 v126, v124, v125
	v_lshl_add_u64 v[244:245], v[244:245], 0, s[46:47]
	v_lshl_add_u64 v[248:249], v[248:249], 0, s[46:47]
	v_lshl_add_u64 v[250:251], v[250:251], 0, s[48:49]

.Lf3_nocwt2CONLY:
	s_or_b64 exec, exec, s[12:13]
	s_waitcnt lgkmcnt(0)
	s_barrier
	v_mfma_f32_32x32x16_bf16 v[14:29], v[190:193], v[226:229], v[14:29]
	v_mfma_f32_32x32x16_bf16 v[30:45], v[194:197], v[226:229], v[30:45]
	global_load_dwordx4 v[114:117], v[242:243], off
	s_and_saveexec_b64 s[12:13], s[6:7]
	s_cbranch_execz .Lf3_nockt2CONLY
	global_load_dword v152, v[250:251], off
.Lf3_nockt2CONLY:
	s_or_b64 exec, exec, s[12:13]
	s_mov_b32 m0, s54
	s_nop 0
	global_load_lds_dwordx4 v[246:247], off
	v_mfma_f32_32x32x16_bf16 v[14:29], v[198:201], v[230:233], v[14:29]
	v_mfma_f32_32x32x16_bf16 v[30:45], v[202:205], v[230:233], v[30:45]
	v_mfma_f32_32x32x16_bf16 v[14:29], v[206:209], v[234:237], v[14:29]
	v_mfma_f32_32x32x16_bf16 v[30:45], v[210:213], v[234:237], v[30:45]
	v_mfma_f32_32x32x16_bf16 v[14:29], v[214:217], v[238:241], v[14:29]
	v_mfma_f32_32x32x16_bf16 v[30:45], v[222:225], v[238:241], v[30:45]
	v_lshl_add_u64 v[242:243], v[242:243], 0, s[46:47]
	v_lshl_add_u64 v[246:247], v[246:247], 0, s[46:47]
	s_branch .Lf3_tail3

.Lf3_nockt2FULL:
	s_or_b64 exec, exec, s[12:13]
	s_mov_b32 m0, s54
	s_nop 0
	global_load_lds_dwordx4 v[246:247], off
	v_max3_f32 v125, v125, v86, v87
	v_max3_f32 v124, v124, v88, v89
	v_max3_f32 v125, v125, v90, v91
	v_mfma_f32_32x32x16_bf16 v[14:29], v[198:201], v[230:233], v[14:29]
	ds_read_b128 v[198:201], v218 offset:32
	v_max3_f32 v124, v124, v92, v93
	v_max3_f32 v125, v125, v94, v95
	v_max3_f32 v124, v124, v96, v97
	v_mfma_f32_32x32x16_bf16 v[30:45], v[202:205], v[230:233], v[30:45]
	ds_read_b128 v[202:205], v218 offset:4640
	v_max3_f32 v125, v125, v98, v99
	v_max3_f32 v124, v124, v100, v101
	v_max3_f32 v125, v125, v102, v103
	v_mfma_f32_32x32x16_bf16 v[14:29], v[206:209], v[234:237], v[14:29]
	ds_read_b128 v[206:209], v218 offset:64
	v_max3_f32 v124, v124, v104, v105
	v_max3_f32 v125, v125, v106, v107
	v_mfma_f32_32x32x16_bf16 v[30:45], v[210:213], v[234:237], v[30:45]
	ds_read_b128 v[210:213], v218 offset:4672
	v_max3_f32 v124, v124, v108, v109
	v_max_f32_e32 v124, v124, v125
	v_mfma_f32_32x32x16_bf16 v[14:29], v[214:217], v[238:241], v[14:29]
	ds_read_b128 v[214:217], v218 offset:96
	v_mov_b32_e32 v125, v124
	s_nop 1
	v_mfma_f32_32x32x16_bf16 v[30:45], v[222:225], v[238:241], v[30:45]
	s_waitcnt lgkmcnt(14)
	ds_read_b128 v[222:225], v218 offset:4704
	v_permlane32_swap_b32_e32 v124, v125
	v_max_f32_e32 v126, v124, v125
	v_lshl_add_u64 v[242:243], v[242:243], 0, s[46:47]
	v_lshl_add_u64 v[246:247], v[246:247], 0, s[46:47]
	s_branch .Lf3_tail3

.Lf3_nocwt2FULLM:
	s_or_b64 exec, exec, s[12:13]
	v_exp_f32_e32 v70, v70
	v_exp_f32_e32 v71, v71
	v_exp_f32_e32 v72, v72
	v_exp_f32_e32 v73, v73
	v_exp_f32_e32 v74, v74
	v_exp_f32_e32 v75, v75
	v_exp_f32_e32 v76, v76
	v_exp_f32_e32 v77, v77
	v_add_f32_e32 v122, v122, v70
	v_add_f32_e32 v123, v123, v71
	v_add_f32_e32 v122, v122, v72
	v_add_f32_e32 v123, v123, v73
	v_add_f32_e32 v122, v122, v74
	v_add_f32_e32 v123, v123, v75
	v_add_f32_e32 v122, v122, v76
	v_add_f32_e32 v123, v123, v77
	v_cvt_pk_bf16_f32 v238, v70, v71
	v_cvt_pk_bf16_f32 v239, v72, v73
	v_cvt_pk_bf16_f32 v240, v74, v75
	v_cvt_pk_bf16_f32 v241, v76, v77
	v_add_f32_e32 v122, v122, v123
	v_add_f32_e32 v161, v161, v122
	s_waitcnt lgkmcnt(0)
	s_barrier
	ds_read_b128 v[46:49], v158 offset:43008
	ds_read_b128 v[50:53], v158 offset:43040
	ds_read_b128 v[54:57], v158 offset:43072
	ds_read_b128 v[58:61], v158 offset:43104
	ds_read_b128 v[62:65], v158 offset:43136
	ds_read_b128 v[66:69], v158 offset:43168
	ds_read_b128 v[70:73], v158 offset:43200
	ds_read_b128 v[74:77], v158 offset:43232
	v_mfma_f32_32x32x16_bf16 v[14:29], v[190:193], v[226:229], v[14:29]
	ds_read_b128 v[190:193], v218
	v_cmp_le_i32_e64 s[52:53], 0, v219
	v_cmp_le_i32_e64 s[14:15], 32, v219
	v_cmp_le_i32_e64 s[16:17], 1, v219
	v_cndmask_b32_e64 v78, v220, v78, s[52:53]
	v_cmp_le_i32_e64 s[52:53], 33, v219
	v_cndmask_b32_e64 v94, v220, v94, s[14:15]
	v_cmp_le_i32_e64 s[14:15], 2, v219
	v_cndmask_b32_e64 v79, v220, v79, s[16:17]
	v_cmp_le_i32_e64 s[16:17], 34, v219
	v_cndmask_b32_e64 v95, v220, v95, s[52:53]
	v_cmp_le_i32_e64 s[52:53], 3, v219
	v_mfma_f32_32x32x16_bf16 v[30:45], v[194:197], v[226:229], v[30:45]
	ds_read_b128 v[194:197], v218 offset:4608
	global_load_dwordx4 v[114:117], v[242:243], off
	s_and_saveexec_b64 s[12:13], s[6:7]
	s_cbranch_execz .Lf3_nockt2FULLM
	global_load_dword v152, v[250:251], off
.Lf3_nockt2FULLM:
	s_or_b64 exec, exec, s[12:13]
	s_mov_b32 m0, s54
	s_nop 0
	global_load_lds_dwordx4 v[246:247], off
	v_cndmask_b32_e64 v80, v220, v80, s[14:15]
	v_cmp_le_i32_e64 s[14:15], 35, v219
	v_cndmask_b32_e64 v96, v220, v96, s[16:17]
	v_cmp_le_i32_e64 s[16:17], 8, v219
	v_cndmask_b32_e64 v81, v220, v81, s[52:53]
	v_cmp_le_i32_e64 s[52:53], 40, v219
	v_cndmask_b32_e64 v97, v220, v97, s[14:15]
	v_cmp_le_i32_e64 s[14:15], 9, v219
	v_cndmask_b32_e64 v82, v220, v82, s[16:17]
	v_cmp_le_i32_e64 s[16:17], 41, v219
	v_cndmask_b32_e64 v98, v220, v98, s[52:53]
	v_mfma_f32_32x32x16_bf16 v[14:29], v[198:201], v[230:233], v[14:29]
	ds_read_b128 v[198:201], v218 offset:32
	v_cmp_le_i32_e64 s[52:53], 10, v219
	v_cndmask_b32_e64 v83, v220, v83, s[14:15]
	v_cmp_le_i32_e64 s[14:15], 42, v219
	v_cndmask_b32_e64 v99, v220, v99, s[16:17]
	v_cmp_le_i32_e64 s[16:17], 11, v219
	v_cndmask_b32_e64 v84, v220, v84, s[52:53]
	v_cmp_le_i32_e64 s[52:53], 43, v219
	v_cndmask_b32_e64 v100, v220, v100, s[14:15]
	v_cmp_le_i32_e64 s[14:15], 16, v219
	v_cndmask_b32_e64 v85, v220, v85, s[16:17]
	v_cmp_le_i32_e64 s[16:17], 48, v219
	v_mfma_f32_32x32x16_bf16 v[30:45], v[202:205], v[230:233], v[30:45]
	ds_read_b128 v[202:205], v218 offset:4640
	v_cndmask_b32_e64 v101, v220, v101, s[52:53]
	v_cmp_le_i32_e64 s[52:53], 17, v219
	v_cndmask_b32_e64 v86, v220, v86, s[14:15]
	v_cmp_le_i32_e64 s[14:15], 49, v219
	v_cndmask_b32_e64 v102, v220, v102, s[16:17]
	v_cmp_le_i32_e64 s[16:17], 18, v219
	v_cndmask_b32_e64 v87, v220, v87, s[52:53]
	v_cmp_le_i32_e64 s[52:53], 50, v219
	v_cndmask_b32_e64 v103, v220, v103, s[14:15]
	v_cmp_le_i32_e64 s[14:15], 19, v219
	v_cndmask_b32_e64 v88, v220, v88, s[16:17]
	v_mfma_f32_32x32x16_bf16 v[14:29], v[206:209], v[234:237], v[14:29]
	ds_read_b128 v[206:209], v218 offset:64
	v_cmp_le_i32_e64 s[16:17], 51, v219
	v_cndmask_b32_e64 v104, v220, v104, s[52:53]
	v_cmp_le_i32_e64 s[52:53], 24, v219
	v_cndmask_b32_e64 v89, v220, v89, s[14:15]
	v_cmp_le_i32_e64 s[14:15], 56, v219
	v_cndmask_b32_e64 v105, v220, v105, s[16:17]
	v_cmp_le_i32_e64 s[16:17], 25, v219
	v_cndmask_b32_e64 v90, v220, v90, s[52:53]
	v_cmp_le_i32_e64 s[52:53], 57, v219
	v_cndmask_b32_e64 v106, v220, v106, s[14:15]
	v_mfma_f32_32x32x16_bf16 v[30:45], v[210:213], v[234:237], v[30:45]
	ds_read_b128 v[210:213], v218 offset:4672
	v_cmp_le_i32_e64 s[14:15], 26, v219
	v_cndmask_b32_e64 v91, v220, v91, s[16:17]
	v_cmp_le_i32_e64 s[16:17], 58, v219
	v_cndmask_b32_e64 v107, v220, v107, s[52:53]
	v_cmp_le_i32_e64 s[52:53], 27, v219
	v_cndmask_b32_e64 v92, v220, v92, s[14:15]
	v_cmp_le_i32_e64 s[14:15], 59, v219
	v_cndmask_b32_e64 v108, v220, v108, s[16:17]
	v_cndmask_b32_e64 v93, v220, v93, s[52:53]
	v_cndmask_b32_e64 v109, v220, v109, s[14:15]
	v_mfma_f32_32x32x16_bf16 v[14:29], v[214:217], v[238:241], v[14:29]
	ds_read_b128 v[214:217], v218 offset:96
	v_max3_f32 v124, v78, v79, v80
	v_max3_f32 v125, v81, v82, v83
	v_max3_f32 v124, v124, v84, v85
	v_max3_f32 v125, v125, v86, v87
	v_max3_f32 v124, v124, v88, v89
	v_max3_f32 v125, v125, v90, v91
	v_max3_f32 v124, v124, v92, v93
	v_max3_f32 v125, v125, v94, v95
	v_max3_f32 v124, v124, v96, v97
	v_max3_f32 v125, v125, v98, v99
	v_mfma_f32_32x32x16_bf16 v[30:45], v[222:225], v[238:241], v[30:45]
	s_waitcnt lgkmcnt(14)
	ds_read_b128 v[222:225], v218 offset:4704
	v_max3_f32 v124, v124, v100, v101
	v_max3_f32 v125, v125, v102, v103
	v_max3_f32 v124, v124, v104, v105
	v_max3_f32 v125, v125, v106, v107
	v_max3_f32 v124, v124, v108, v109
	v_max_f32_e32 v124, v124, v125
	v_mov_b32_e32 v125, v124
	s_nop 1
	v_permlane32_swap_b32_e32 v124, v125
	v_max_f32_e32 v126, v124, v125
	v_lshl_add_u64 v[242:243], v[242:243], 0, s[46:47]
	v_lshl_add_u64 v[246:247], v[246:247], 0, s[46:47]

.Lf3_nocwt3IDLE:
	s_or_b64 exec, exec, s[12:13]
	s_waitcnt lgkmcnt(0)
	s_barrier
	s_mov_b32 m0, s55
	s_nop 0
	global_load_lds_dwordx4 v[248:249], off
	v_lshl_add_u64 v[244:245], v[244:245], 0, s[46:47]
	v_lshl_add_u64 v[248:249], v[248:249], 0, s[46:47]
	v_lshl_add_u64 v[250:251], v[250:251], 0, s[48:49]
	s_branch .Lf3_tail4

.Lf3_nocwt3FULL:
	s_or_b64 exec, exec, s[12:13]
	v_exp_f32_e32 v102, v102
	v_exp_f32_e32 v103, v103
	v_exp_f32_e32 v104, v104
	v_exp_f32_e32 v105, v105
	v_exp_f32_e32 v106, v106
	v_exp_f32_e32 v107, v107
	v_exp_f32_e32 v108, v108
	v_exp_f32_e32 v109, v109
	v_add_f32_e32 v122, v122, v102
	v_add_f32_e32 v123, v123, v103
	v_add_f32_e32 v122, v122, v104
	v_add_f32_e32 v123, v123, v105
	v_add_f32_e32 v122, v122, v106
	v_add_f32_e32 v123, v123, v107
	v_add_f32_e32 v122, v122, v108
	v_add_f32_e32 v123, v123, v109
	v_cvt_pk_bf16_f32 v238, v102, v103
	v_cvt_pk_bf16_f32 v239, v104, v105
	v_cvt_pk_bf16_f32 v240, v106, v107
	v_cvt_pk_bf16_f32 v241, v108, v109
	v_add_f32_e32 v122, v122, v123
	v_add_f32_e32 v161, v161, v122
	s_waitcnt lgkmcnt(0)
	s_barrier
	ds_read_b128 v[78:81], v158 offset:43264
	ds_read_b128 v[82:85], v158 offset:43296
	ds_read_b128 v[86:89], v158 offset:43328
	ds_read_b128 v[90:93], v158 offset:43360
	ds_read_b128 v[94:97], v158 offset:43392
	ds_read_b128 v[98:101], v158 offset:43424
	ds_read_b128 v[102:105], v158 offset:43456
	ds_read_b128 v[106:109], v158 offset:43488
	v_mfma_f32_32x32x16_bf16 v[14:29], v[190:193], v[226:229], v[14:29]
	ds_read_b128 v[190:193], v218 offset:13312
	v_max3_f32 v124, v46, v47, v48
	v_max3_f32 v125, v49, v50, v51
	v_max3_f32 v124, v124, v52, v53
	v_mfma_f32_32x32x16_bf16 v[30:45], v[194:197], v[226:229], v[30:45]
	ds_read_b128 v[194:197], v218 offset:17920
	s_mov_b32 m0, s55
	s_nop 0
	global_load_lds_dwordx4 v[248:249], off
	v_max3_f32 v125, v125, v54, v55
	v_max3_f32 v124, v124, v56, v57
	v_max3_f32 v125, v125, v58, v59
	v_mfma_f32_32x32x16_bf16 v[14:29], v[198:201], v[230:233], v[14:29]
	ds_read_b128 v[198:201], v218 offset:13344
	v_max3_f32 v124, v124, v60, v61
	v_max3_f32 v125, v125, v62, v63
	v_max3_f32 v124, v124, v64, v65
	v_mfma_f32_32x32x16_bf16 v[30:45], v[202:205], v[230:233], v[30:45]
	ds_read_b128 v[202:205], v218 offset:17952
	v_max3_f32 v125, v125, v66, v67
	v_max3_f32 v124, v124, v68, v69
	v_max3_f32 v125, v125, v70, v71
	v_mfma_f32_32x32x16_bf16 v[14:29], v[206:209], v[234:237], v[14:29]
	ds_read_b128 v[206:209], v218 offset:13376
	v_max3_f32 v124, v124, v72, v73
	v_max3_f32 v125, v125, v74, v75
	v_mfma_f32_32x32x16_bf16 v[30:45], v[210:213], v[234:237], v[30:45]
	ds_read_b128 v[210:213], v218 offset:17984
	v_max3_f32 v124, v124, v76, v77
	v_max_f32_e32 v124, v124, v125
	v_mfma_f32_32x32x16_bf16 v[14:29], v[214:217], v[238:241], v[14:29]
	ds_read_b128 v[214:217], v218 offset:13408
	v_mov_b32_e32 v125, v124
	s_nop 1
	v_mfma_f32_32x32x16_bf16 v[30:45], v[222:225], v[238:241], v[30:45]
	s_waitcnt lgkmcnt(14)
	ds_read_b128 v[222:225], v218 offset:18016
	v_permlane32_swap_b32_e32 v124, v125
	v_max_f32_e32 v126, v124, v125
	v_lshl_add_u64 v[244:245], v[244:245], 0, s[46:47]
	v_lshl_add_u64 v[248:249], v[248:249], 0, s[46:47]
	v_lshl_add_u64 v[250:251], v[250:251], 0, s[48:49]
	s_branch .Lf3_tail4

.Lf3_nocwt3FULLM:
	s_or_b64 exec, exec, s[12:13]
	v_exp_f32_e32 v102, v102
	v_exp_f32_e32 v103, v103
	v_exp_f32_e32 v104, v104
	v_exp_f32_e32 v105, v105
	v_exp_f32_e32 v106, v106
	v_exp_f32_e32 v107, v107
	v_exp_f32_e32 v108, v108
	v_exp_f32_e32 v109, v109
	v_add_f32_e32 v122, v122, v102
	v_add_f32_e32 v123, v123, v103
	v_add_f32_e32 v122, v122, v104
	v_add_f32_e32 v123, v123, v105
	v_add_f32_e32 v122, v122, v106
	v_add_f32_e32 v123, v123, v107
	v_add_f32_e32 v122, v122, v108
	v_add_f32_e32 v123, v123, v109
	v_cvt_pk_bf16_f32 v238, v102, v103
	v_cvt_pk_bf16_f32 v239, v104, v105
	v_cvt_pk_bf16_f32 v240, v106, v107
	v_cvt_pk_bf16_f32 v241, v108, v109
	v_add_f32_e32 v122, v122, v123
	v_add_f32_e32 v161, v161, v122
	s_waitcnt lgkmcnt(0)
	s_barrier
	ds_read_b128 v[78:81], v158 offset:43264
	ds_read_b128 v[82:85], v158 offset:43296
	ds_read_b128 v[86:89], v158 offset:43328
	ds_read_b128 v[90:93], v158 offset:43360
	ds_read_b128 v[94:97], v158 offset:43392
	ds_read_b128 v[98:101], v158 offset:43424
	ds_read_b128 v[102:105], v158 offset:43456
	ds_read_b128 v[106:109], v158 offset:43488
	v_mfma_f32_32x32x16_bf16 v[14:29], v[190:193], v[226:229], v[14:29]
	ds_read_b128 v[190:193], v218 offset:13312
	v_cmp_le_i32_e64 s[52:53], 0, v219
	v_cmp_le_i32_e64 s[14:15], 32, v219
	v_cmp_le_i32_e64 s[16:17], 1, v219
	v_cndmask_b32_e64 v46, v220, v46, s[52:53]
	v_cmp_le_i32_e64 s[52:53], 33, v219
	v_cndmask_b32_e64 v62, v220, v62, s[14:15]
	v_cmp_le_i32_e64 s[14:15], 2, v219
	v_cndmask_b32_e64 v47, v220, v47, s[16:17]
	v_cmp_le_i32_e64 s[16:17], 34, v219
	v_cndmask_b32_e64 v63, v220, v63, s[52:53]
	v_cmp_le_i32_e64 s[52:53], 3, v219
	v_mfma_f32_32x32x16_bf16 v[30:45], v[194:197], v[226:229], v[30:45]
	ds_read_b128 v[194:197], v218 offset:17920
	s_mov_b32 m0, s55
	s_nop 0
	global_load_lds_dwordx4 v[248:249], off
	v_cndmask_b32_e64 v48, v220, v48, s[14:15]
	v_cmp_le_i32_e64 s[14:15], 35, v219
	v_cndmask_b32_e64 v64, v220, v64, s[16:17]
	v_cmp_le_i32_e64 s[16:17], 8, v219
	v_cndmask_b32_e64 v49, v220, v49, s[52:53]
	v_cmp_le_i32_e64 s[52:53], 40, v219
	v_cndmask_b32_e64 v65, v220, v65, s[14:15]
	v_cmp_le_i32_e64 s[14:15], 9, v219
	v_cndmask_b32_e64 v50, v220, v50, s[16:17]
	v_cmp_le_i32_e64 s[16:17], 41, v219
	v_cndmask_b32_e64 v66, v220, v66, s[52:53]
	v_mfma_f32_32x32x16_bf16 v[14:29], v[198:201], v[230:233], v[14:29]
	ds_read_b128 v[198:201], v218 offset:13344
	v_cmp_le_i32_e64 s[52:53], 10, v219
	v_cndmask_b32_e64 v51, v220, v51, s[14:15]
	v_cmp_le_i32_e64 s[14:15], 42, v219
	v_cndmask_b32_e64 v67, v220, v67, s[16:17]
	v_cmp_le_i32_e64 s[16:17], 11, v219
	v_cndmask_b32_e64 v52, v220, v52, s[52:53]
	v_cmp_le_i32_e64 s[52:53], 43, v219
	v_cndmask_b32_e64 v68, v220, v68, s[14:15]
	v_cmp_le_i32_e64 s[14:15], 16, v219
	v_cndmask_b32_e64 v53, v220, v53, s[16:17]
	v_cmp_le_i32_e64 s[16:17], 48, v219
	v_mfma_f32_32x32x16_bf16 v[30:45], v[202:205], v[230:233], v[30:45]
	ds_read_b128 v[202:205], v218 offset:17952
	v_cndmask_b32_e64 v69, v220, v69, s[52:53]
	v_cmp_le_i32_e64 s[52:53], 17, v219
	v_cndmask_b32_e64 v54, v220, v54, s[14:15]
	v_cmp_le_i32_e64 s[14:15], 49, v219
	v_cndmask_b32_e64 v70, v220, v70, s[16:17]
	v_cmp_le_i32_e64 s[16:17], 18, v219
	v_cndmask_b32_e64 v55, v220, v55, s[52:53]
	v_cmp_le_i32_e64 s[52:53], 50, v219
	v_cndmask_b32_e64 v71, v220, v71, s[14:15]
	v_cmp_le_i32_e64 s[14:15], 19, v219
	v_cndmask_b32_e64 v56, v220, v56, s[16:17]
	v_mfma_f32_32x32x16_bf16 v[14:29], v[206:209], v[234:237], v[14:29]
	ds_read_b128 v[206:209], v218 offset:13376
	v_cmp_le_i32_e64 s[16:17], 51, v219
	v_cndmask_b32_e64 v72, v220, v72, s[52:53]
	v_cmp_le_i32_e64 s[52:53], 24, v219
	v_cndmask_b32_e64 v57, v220, v57, s[14:15]
	v_cmp_le_i32_e64 s[14:15], 56, v219
	v_cndmask_b32_e64 v73, v220, v73, s[16:17]
	v_cmp_le_i32_e64 s[16:17], 25, v219
	v_cndmask_b32_e64 v58, v220, v58, s[52:53]
	v_cmp_le_i32_e64 s[52:53], 57, v219
	v_cndmask_b32_e64 v74, v220, v74, s[14:15]
	v_mfma_f32_32x32x16_bf16 v[30:45], v[210:213], v[234:237], v[30:45]
	ds_read_b128 v[210:213], v218 offset:17984
	v_cmp_le_i32_e64 s[14:15], 26, v219
	v_cndmask_b32_e64 v59, v220, v59, s[16:17]
	v_cmp_le_i32_e64 s[16:17], 58, v219
	v_cndmask_b32_e64 v75, v220, v75, s[52:53]
	v_cmp_le_i32_e64 s[52:53], 27, v219
	v_cndmask_b32_e64 v60, v220, v60, s[14:15]
	v_cmp_le_i32_e64 s[14:15], 59, v219
	v_cndmask_b32_e64 v76, v220, v76, s[16:17]
	v_cndmask_b32_e64 v61, v220, v61, s[52:53]
	v_cndmask_b32_e64 v77, v220, v77, s[14:15]
	v_mfma_f32_32x32x16_bf16 v[14:29], v[214:217], v[238:241], v[14:29]
	ds_read_b128 v[214:217], v218 offset:13408
	v_max3_f32 v124, v46, v47, v48
	v_max3_f32 v125, v49, v50, v51
	v_max3_f32 v124, v124, v52, v53
	v_max3_f32 v125, v125, v54, v55
	v_max3_f32 v124, v124, v56, v57
	v_max3_f32 v125, v125, v58, v59
	v_max3_f32 v124, v124, v60, v61
	v_max3_f32 v125, v125, v62, v63
	v_max3_f32 v124, v124, v64, v65
	v_max3_f32 v125, v125, v66, v67
	v_mfma_f32_32x32x16_bf16 v[30:45], v[222:225], v[238:241], v[30:45]
	s_waitcnt lgkmcnt(14)
	ds_read_b128 v[222:225], v218 offset:18016
	v_max3_f32 v124, v124, v68, v69
	v_max3_f32 v125, v125, v70, v71
	v_max3_f32 v124, v124, v72, v73
	v_max3_f32 v125, v125, v74, v75
	v_max3_f32 v124, v124, v76, v77
	v_max_f32_e32 v124, v124, v125
	v_mov_b32_e32 v125, v124
	s_nop 1
	v_permlane32_swap_b32_e32 v124, v125
	v_max_f32_e32 v126, v124, v125
	v_lshl_add_u64 v[244:245], v[244:245], 0, s[46:47]
	v_lshl_add_u64 v[248:249], v[248:249], 0, s[46:47]
	v_lshl_add_u64 v[250:251], v[250:251], 0, s[48:49]
	s_branch .Lf3_tail4

.Lf3_nocwt3CONLY:
	s_or_b64 exec, exec, s[12:13]
	s_waitcnt lgkmcnt(0)
	s_barrier
	v_mfma_f32_32x32x16_bf16 v[14:29], v[190:193], v[226:229], v[14:29]
	v_mfma_f32_32x32x16_bf16 v[30:45], v[194:197], v[226:229], v[30:45]
	s_mov_b32 m0, s55
	s_nop 0
	global_load_lds_dwordx4 v[248:249], off
	v_mfma_f32_32x32x16_bf16 v[14:29], v[198:201], v[230:233], v[14:29]
	v_mfma_f32_32x32x16_bf16 v[30:45], v[202:205], v[230:233], v[30:45]
	v_mfma_f32_32x32x16_bf16 v[14:29], v[206:209], v[234:237], v[14:29]
	v_mfma_f32_32x32x16_bf16 v[30:45], v[210:213], v[234:237], v[30:45]
	v_mfma_f32_32x32x16_bf16 v[14:29], v[214:217], v[238:241], v[14:29]
	v_mfma_f32_32x32x16_bf16 v[30:45], v[222:225], v[238:241], v[30:45]
	v_lshl_add_u64 v[244:245], v[244:245], 0, s[46:47]
	v_lshl_add_u64 v[248:249], v[248:249], 0, s[46:47]
	v_lshl_add_u64 v[250:251], v[250:251], 0, s[48:49]
.Lf3_tail4:
	s_cmp_eq_u32 s11, 3
	s_cbranch_scc1 .Lf3_t4_FULLM
	s_cmp_eq_u32 s11, 2
	s_cbranch_scc1 .Lf3_t4_CONLY
	s_waitcnt lgkmcnt(0)
	s_waitcnt vmcnt(0)
	s_waitcnt lgkmcnt(0)
	s_barrier
	v_lshl_add_u64 v[242:243], v[242:243], 0, s[46:47]
	v_lshl_add_u64 v[246:247], v[246:247], 0, s[46:47]
	s_branch .Lf3_tail5

.Lf3_resc_rett4FULLM:
	s_waitcnt lgkmcnt(7)
	v_mfma_f32_32x32x16_bf16 v[78:93], v[190:193], v[0:3], v[78:93]
	ds_read_b64_tr_b16 v[190:191], v159 offset:26624
	ds_read_b64_tr_b16 v[192:193], v159 offset:27136
	v_sub_f32_e32 v46, v46, v160
	v_sub_f32_e32 v47, v47, v160
	v_sub_f32_e32 v48, v48, v160
	v_sub_f32_e32 v49, v49, v160
	v_sub_f32_e32 v50, v50, v160
	v_sub_f32_e32 v51, v51, v160
	v_sub_f32_e32 v52, v52, v160
	v_sub_f32_e32 v53, v53, v160
	v_exp_f32_e32 v46, v46
	v_exp_f32_e32 v47, v47
	v_exp_f32_e32 v48, v48
	v_exp_f32_e32 v49, v49
	s_waitcnt lgkmcnt(8)
	v_mfma_f32_32x32x16_bf16 v[94:109], v[194:197], v[0:3], v[94:109]
	ds_read_b64_tr_b16 v[194:195], v159 offset:30720
	ds_read_b64_tr_b16 v[196:197], v159 offset:31232
	v_exp_f32_e32 v50, v50
	v_exp_f32_e32 v51, v51
	v_exp_f32_e32 v52, v52
	v_exp_f32_e32 v53, v53
	v_add_f32_e32 v122, v46, v47
	v_add_f32_e32 v123, v48, v49
	v_add_f32_e32 v122, v122, v50
	v_add_f32_e32 v123, v123, v51
	v_add_f32_e32 v122, v122, v52
	v_add_f32_e32 v123, v123, v53
	v_cvt_pk_bf16_f32 v226, v46, v47
	v_cvt_pk_bf16_f32 v227, v48, v49
	s_waitcnt lgkmcnt(9)
	v_mfma_f32_32x32x16_bf16 v[78:93], v[198:201], v[4:7], v[78:93]
	ds_read_b64_tr_b16 v[198:199], v159 offset:27648
	ds_read_b64_tr_b16 v[200:201], v159 offset:28160
	v_cvt_pk_bf16_f32 v228, v50, v51
	v_cvt_pk_bf16_f32 v229, v52, v53
	v_sub_f32_e32 v54, v54, v160
	v_sub_f32_e32 v55, v55, v160
	v_sub_f32_e32 v56, v56, v160
	v_sub_f32_e32 v57, v57, v160
	v_sub_f32_e32 v58, v58, v160
	v_sub_f32_e32 v59, v59, v160
	v_sub_f32_e32 v60, v60, v160
	v_sub_f32_e32 v61, v61, v160
	v_exp_f32_e32 v54, v54
	s_waitcnt lgkmcnt(10)
	v_mfma_f32_32x32x16_bf16 v[94:109], v[202:205], v[4:7], v[94:109]
	ds_read_b64_tr_b16 v[202:203], v159 offset:31744
	ds_read_b64_tr_b16 v[204:205], v159 offset:32256
	v_exp_f32_e32 v55, v55
	v_exp_f32_e32 v56, v56
	v_exp_f32_e32 v57, v57
	v_exp_f32_e32 v58, v58
	v_exp_f32_e32 v59, v59
	v_exp_f32_e32 v60, v60
	v_exp_f32_e32 v61, v61
	v_add_f32_e32 v122, v122, v54
	v_add_f32_e32 v123, v123, v55
	v_add_f32_e32 v122, v122, v56
	v_add_f32_e32 v123, v123, v57
	s_waitcnt lgkmcnt(11)
	v_mfma_f32_32x32x16_bf16 v[78:93], v[206:209], v[8:11], v[78:93]
	ds_read_b64_tr_b16 v[206:207], v159 offset:28672
	ds_read_b64_tr_b16 v[208:209], v159 offset:29184
	v_add_f32_e32 v122, v122, v58
	v_add_f32_e32 v123, v123, v59
	v_add_f32_e32 v122, v122, v60
	v_add_f32_e32 v123, v123, v61
	v_cvt_pk_bf16_f32 v230, v54, v55
	v_cvt_pk_bf16_f32 v231, v56, v57
	v_cvt_pk_bf16_f32 v232, v58, v59
	v_cvt_pk_bf16_f32 v233, v60, v61
	v_sub_f32_e32 v62, v62, v160
	v_sub_f32_e32 v63, v63, v160
	v_sub_f32_e32 v64, v64, v160
	s_waitcnt lgkmcnt(12)
	v_mfma_f32_32x32x16_bf16 v[94:109], v[210:213], v[8:11], v[94:109]
	ds_read_b64_tr_b16 v[210:211], v159 offset:32768
	ds_read_b64_tr_b16 v[212:213], v159 offset:33280
	v_sub_f32_e32 v65, v65, v160
	v_sub_f32_e32 v66, v66, v160
	v_sub_f32_e32 v67, v67, v160
	v_sub_f32_e32 v68, v68, v160
	v_sub_f32_e32 v69, v69, v160
	v_exp_f32_e32 v62, v62
	v_exp_f32_e32 v63, v63
	v_exp_f32_e32 v64, v64
	v_exp_f32_e32 v65, v65
	v_exp_f32_e32 v66, v66
	v_exp_f32_e32 v67, v67
	s_waitcnt lgkmcnt(13)
	v_mfma_f32_32x32x16_bf16 v[78:93], v[214:217], v[110:113], v[78:93]
	ds_read_b64_tr_b16 v[214:215], v159 offset:29696
	ds_read_b64_tr_b16 v[216:217], v159 offset:30208
	v_exp_f32_e32 v68, v68
	v_exp_f32_e32 v69, v69
	v_add_f32_e32 v122, v122, v62
	v_add_f32_e32 v123, v123, v63
	v_add_f32_e32 v122, v122, v64
	v_add_f32_e32 v123, v123, v65
	v_add_f32_e32 v122, v122, v66
	v_add_f32_e32 v123, v123, v67
	v_add_f32_e32 v122, v122, v68
	v_add_f32_e32 v123, v123, v69
	v_cvt_pk_bf16_f32 v234, v62, v63
	s_waitcnt lgkmcnt(14)
	v_mfma_f32_32x32x16_bf16 v[94:109], v[222:225], v[110:113], v[94:109]
	s_waitcnt lgkmcnt(13)
	ds_read_b64_tr_b16 v[222:223], v159 offset:33792
	ds_read_b64_tr_b16 v[224:225], v159 offset:34304
	v_cvt_pk_bf16_f32 v235, v64, v65
	v_cvt_pk_bf16_f32 v236, v66, v67
	v_cvt_pk_bf16_f32 v237, v68, v69
	v_sub_f32_e32 v70, v70, v160
	v_sub_f32_e32 v71, v71, v160
	v_sub_f32_e32 v72, v72, v160
	v_sub_f32_e32 v73, v73, v160
	v_sub_f32_e32 v74, v74, v160
	v_sub_f32_e32 v75, v75, v160
	v_sub_f32_e32 v76, v76, v160
	v_sub_f32_e32 v77, v77, v160
	s_waitcnt lgkmcnt(8)
	s_waitcnt vmcnt(0)
	v_exp_f32_e32 v70, v70
	v_exp_f32_e32 v71, v71
	v_exp_f32_e32 v72, v72
	v_exp_f32_e32 v73, v73
	v_exp_f32_e32 v74, v74
	v_exp_f32_e32 v75, v75
	v_exp_f32_e32 v76, v76
	v_exp_f32_e32 v77, v77
	v_add_f32_e32 v122, v122, v70
	v_add_f32_e32 v123, v123, v71
	v_add_f32_e32 v122, v122, v72
	v_add_f32_e32 v123, v123, v73
	v_add_f32_e32 v122, v122, v74
	v_add_f32_e32 v123, v123, v75
	v_add_f32_e32 v122, v122, v76
	v_add_f32_e32 v123, v123, v77
	v_cvt_pk_bf16_f32 v238, v70, v71
	v_cvt_pk_bf16_f32 v239, v72, v73
	v_cvt_pk_bf16_f32 v240, v74, v75
	v_cvt_pk_bf16_f32 v241, v76, v77
	v_add_f32_e32 v122, v122, v123
	v_add_f32_e32 v161, v161, v122
	s_waitcnt lgkmcnt(0)
	s_barrier
	ds_read_b128 v[46:49], v158 offset:43008
	ds_read_b128 v[50:53], v158 offset:43040
	ds_read_b128 v[54:57], v158 offset:43072
	ds_read_b128 v[58:61], v158 offset:43104
	ds_read_b128 v[62:65], v158 offset:43136
	ds_read_b128 v[66:69], v158 offset:43168
	ds_read_b128 v[70:73], v158 offset:43200
	ds_read_b128 v[74:77], v158 offset:43232
	v_mfma_f32_32x32x16_bf16 v[14:29], v[190:193], v[226:229], v[14:29]
	ds_read_b128 v[190:193], v218
	v_cmp_le_i32_e64 s[52:53], 0, v219
	v_cmp_le_i32_e64 s[14:15], 32, v219
	v_cmp_le_i32_e64 s[16:17], 1, v219
	v_cndmask_b32_e64 v78, v220, v78, s[52:53]
	v_cmp_le_i32_e64 s[52:53], 33, v219
	v_cndmask_b32_e64 v94, v220, v94, s[14:15]
	v_cmp_le_i32_e64 s[14:15], 2, v219
	v_cndmask_b32_e64 v79, v220, v79, s[16:17]
	v_cmp_le_i32_e64 s[16:17], 34, v219
	v_cndmask_b32_e64 v95, v220, v95, s[52:53]
	v_cmp_le_i32_e64 s[52:53], 3, v219
	v_mfma_f32_32x32x16_bf16 v[30:45], v[194:197], v[226:229], v[30:45]
	ds_read_b128 v[194:197], v218 offset:4608
	v_cndmask_b32_e64 v80, v220, v80, s[14:15]
	v_cmp_le_i32_e64 s[14:15], 35, v219
	v_cndmask_b32_e64 v96, v220, v96, s[16:17]
	v_cmp_le_i32_e64 s[16:17], 8, v219
	v_cndmask_b32_e64 v81, v220, v81, s[52:53]
	v_cmp_le_i32_e64 s[52:53], 40, v219
	v_cndmask_b32_e64 v97, v220, v97, s[14:15]
	v_cmp_le_i32_e64 s[14:15], 9, v219
	v_cndmask_b32_e64 v82, v220, v82, s[16:17]
	v_cmp_le_i32_e64 s[16:17], 41, v219
	v_cndmask_b32_e64 v98, v220, v98, s[52:53]
	v_mfma_f32_32x32x16_bf16 v[14:29], v[198:201], v[230:233], v[14:29]
	ds_read_b128 v[198:201], v218 offset:32
	v_cmp_le_i32_e64 s[52:53], 10, v219
	v_cndmask_b32_e64 v83, v220, v83, s[14:15]
	v_cmp_le_i32_e64 s[14:15], 42, v219
	v_cndmask_b32_e64 v99, v220, v99, s[16:17]
	v_cmp_le_i32_e64 s[16:17], 11, v219
	v_cndmask_b32_e64 v84, v220, v84, s[52:53]
	v_cmp_le_i32_e64 s[52:53], 43, v219
	v_cndmask_b32_e64 v100, v220, v100, s[14:15]
	v_cmp_le_i32_e64 s[14:15], 16, v219
	v_cndmask_b32_e64 v85, v220, v85, s[16:17]
	v_cmp_le_i32_e64 s[16:17], 48, v219
	v_mfma_f32_32x32x16_bf16 v[30:45], v[202:205], v[230:233], v[30:45]
	ds_read_b128 v[202:205], v218 offset:4640
	v_cndmask_b32_e64 v101, v220, v101, s[52:53]
	v_cmp_le_i32_e64 s[52:53], 17, v219
	v_cndmask_b32_e64 v86, v220, v86, s[14:15]
	v_cmp_le_i32_e64 s[14:15], 49, v219
	v_cndmask_b32_e64 v102, v220, v102, s[16:17]
	v_cmp_le_i32_e64 s[16:17], 18, v219
	v_cndmask_b32_e64 v87, v220, v87, s[52:53]
	v_cmp_le_i32_e64 s[52:53], 50, v219
	v_cndmask_b32_e64 v103, v220, v103, s[14:15]
	v_cmp_le_i32_e64 s[14:15], 19, v219
	v_cndmask_b32_e64 v88, v220, v88, s[16:17]
	v_mfma_f32_32x32x16_bf16 v[14:29], v[206:209], v[234:237], v[14:29]
	ds_read_b128 v[206:209], v218 offset:64
	v_cmp_le_i32_e64 s[16:17], 51, v219
	v_cndmask_b32_e64 v104, v220, v104, s[52:53]
	v_cmp_le_i32_e64 s[52:53], 24, v219
	v_cndmask_b32_e64 v89, v220, v89, s[14:15]
	v_cmp_le_i32_e64 s[14:15], 56, v219
	v_cndmask_b32_e64 v105, v220, v105, s[16:17]
	v_cmp_le_i32_e64 s[16:17], 25, v219
	v_cndmask_b32_e64 v90, v220, v90, s[52:53]
	v_cmp_le_i32_e64 s[52:53], 57, v219
	v_cndmask_b32_e64 v106, v220, v106, s[14:15]
	v_mfma_f32_32x32x16_bf16 v[30:45], v[210:213], v[234:237], v[30:45]
	ds_read_b128 v[210:213], v218 offset:4672
	v_cmp_le_i32_e64 s[14:15], 26, v219
	v_cndmask_b32_e64 v91, v220, v91, s[16:17]
	v_cmp_le_i32_e64 s[16:17], 58, v219
	v_cndmask_b32_e64 v107, v220, v107, s[52:53]
	v_cmp_le_i32_e64 s[52:53], 27, v219
	v_cndmask_b32_e64 v92, v220, v92, s[14:15]
	v_cmp_le_i32_e64 s[14:15], 59, v219
	v_cndmask_b32_e64 v108, v220, v108, s[16:17]
	v_cndmask_b32_e64 v93, v220, v93, s[52:53]
	v_cndmask_b32_e64 v109, v220, v109, s[14:15]
	v_mfma_f32_32x32x16_bf16 v[14:29], v[214:217], v[238:241], v[14:29]
	ds_read_b128 v[214:217], v218 offset:96
	v_max3_f32 v124, v78, v79, v80
	v_max3_f32 v125, v81, v82, v83
	v_max3_f32 v124, v124, v84, v85
	v_max3_f32 v125, v125, v86, v87
	v_max3_f32 v124, v124, v88, v89
	v_max3_f32 v125, v125, v90, v91
	v_max3_f32 v124, v124, v92, v93
	v_max3_f32 v125, v125, v94, v95
	v_max3_f32 v124, v124, v96, v97
	v_max3_f32 v125, v125, v98, v99
	v_mfma_f32_32x32x16_bf16 v[30:45], v[222:225], v[238:241], v[30:45]
	s_waitcnt lgkmcnt(14)
	ds_read_b128 v[222:225], v218 offset:4704
	v_max3_f32 v124, v124, v100, v101
	v_max3_f32 v125, v125, v102, v103
	v_max3_f32 v124, v124, v104, v105
	v_max3_f32 v125, v125, v106, v107
	v_max3_f32 v124, v124, v108, v109
	v_max_f32_e32 v124, v124, v125
	v_mov_b32_e32 v125, v124
	s_nop 1
	v_permlane32_swap_b32_e32 v124, v125
	v_max_f32_e32 v126, v124, v125
	v_lshl_add_u64 v[242:243], v[242:243], 0, s[46:47]
	v_lshl_add_u64 v[246:247], v[246:247], 0, s[46:47]
	s_branch .Lf3_tail5

.Lf3_resc_rett4CONLY:
	s_waitcnt lgkmcnt(0)
	ds_read_b64_tr_b16 v[190:191], v159 offset:26624
	ds_read_b64_tr_b16 v[192:193], v159 offset:27136
	ds_read_b64_tr_b16 v[194:195], v159 offset:30720
	ds_read_b64_tr_b16 v[196:197], v159 offset:31232
	ds_read_b64_tr_b16 v[198:199], v159 offset:27648
	ds_read_b64_tr_b16 v[200:201], v159 offset:28160
	ds_read_b64_tr_b16 v[202:203], v159 offset:31744
	ds_read_b64_tr_b16 v[204:205], v159 offset:32256
	ds_read_b64_tr_b16 v[206:207], v159 offset:28672
	ds_read_b64_tr_b16 v[208:209], v159 offset:29184
	ds_read_b64_tr_b16 v[210:211], v159 offset:32768
	ds_read_b64_tr_b16 v[212:213], v159 offset:33280
	ds_read_b64_tr_b16 v[214:215], v159 offset:29696
	ds_read_b64_tr_b16 v[216:217], v159 offset:30208
	v_sub_f32_e32 v46, v46, v160
	v_sub_f32_e32 v47, v47, v160
	v_sub_f32_e32 v48, v48, v160
	v_sub_f32_e32 v49, v49, v160
	v_sub_f32_e32 v50, v50, v160
	v_sub_f32_e32 v51, v51, v160
	v_sub_f32_e32 v52, v52, v160
	v_sub_f32_e32 v53, v53, v160
	v_exp_f32_e32 v46, v46
	v_exp_f32_e32 v47, v47
	v_exp_f32_e32 v48, v48
	v_exp_f32_e32 v49, v49
	v_exp_f32_e32 v50, v50
	v_exp_f32_e32 v51, v51
	v_exp_f32_e32 v52, v52
	v_exp_f32_e32 v53, v53
	v_add_f32_e32 v122, v46, v47
	v_add_f32_e32 v123, v48, v49
	v_add_f32_e32 v122, v122, v50
	v_add_f32_e32 v123, v123, v51
	v_add_f32_e32 v122, v122, v52
	v_add_f32_e32 v123, v123, v53
	v_cvt_pk_bf16_f32 v226, v46, v47
	v_cvt_pk_bf16_f32 v227, v48, v49
	v_cvt_pk_bf16_f32 v228, v50, v51
	v_cvt_pk_bf16_f32 v229, v52, v53
	v_sub_f32_e32 v54, v54, v160
	v_sub_f32_e32 v55, v55, v160
	v_sub_f32_e32 v56, v56, v160
	v_sub_f32_e32 v57, v57, v160
	v_sub_f32_e32 v58, v58, v160
	v_sub_f32_e32 v59, v59, v160
	v_sub_f32_e32 v60, v60, v160
	v_sub_f32_e32 v61, v61, v160
	v_exp_f32_e32 v54, v54
	v_exp_f32_e32 v55, v55
	v_exp_f32_e32 v56, v56
	v_exp_f32_e32 v57, v57
	v_exp_f32_e32 v58, v58
	v_exp_f32_e32 v59, v59
	v_exp_f32_e32 v60, v60
	v_exp_f32_e32 v61, v61
	v_add_f32_e32 v122, v122, v54
	v_add_f32_e32 v123, v123, v55
	v_add_f32_e32 v122, v122, v56
	v_add_f32_e32 v123, v123, v57
	v_add_f32_e32 v122, v122, v58
	v_add_f32_e32 v123, v123, v59
	v_add_f32_e32 v122, v122, v60
	v_add_f32_e32 v123, v123, v61
	v_cvt_pk_bf16_f32 v230, v54, v55
	v_cvt_pk_bf16_f32 v231, v56, v57
	v_cvt_pk_bf16_f32 v232, v58, v59
	v_cvt_pk_bf16_f32 v233, v60, v61
	v_sub_f32_e32 v62, v62, v160
	v_sub_f32_e32 v63, v63, v160
	v_sub_f32_e32 v64, v64, v160
	v_sub_f32_e32 v65, v65, v160
	v_sub_f32_e32 v66, v66, v160
	v_sub_f32_e32 v67, v67, v160
	v_sub_f32_e32 v68, v68, v160
	v_sub_f32_e32 v69, v69, v160
	v_exp_f32_e32 v62, v62
	v_exp_f32_e32 v63, v63
	v_exp_f32_e32 v64, v64
	v_exp_f32_e32 v65, v65
	v_exp_f32_e32 v66, v66
	v_exp_f32_e32 v67, v67
	v_exp_f32_e32 v68, v68
	v_exp_f32_e32 v69, v69
	v_add_f32_e32 v122, v122, v62
	v_add_f32_e32 v123, v123, v63
	v_add_f32_e32 v122, v122, v64
	v_add_f32_e32 v123, v123, v65
	v_add_f32_e32 v122, v122, v66
	v_add_f32_e32 v123, v123, v67
	v_add_f32_e32 v122, v122, v68
	v_add_f32_e32 v123, v123, v69
	v_cvt_pk_bf16_f32 v234, v62, v63
	v_cvt_pk_bf16_f32 v235, v64, v65
	v_cvt_pk_bf16_f32 v236, v66, v67
	v_cvt_pk_bf16_f32 v237, v68, v69
	v_sub_f32_e32 v70, v70, v160
	v_sub_f32_e32 v71, v71, v160
	v_sub_f32_e32 v72, v72, v160
	v_sub_f32_e32 v73, v73, v160
	v_sub_f32_e32 v74, v74, v160
	v_sub_f32_e32 v75, v75, v160
	v_sub_f32_e32 v76, v76, v160
	v_sub_f32_e32 v77, v77, v160
	v_exp_f32_e32 v70, v70
	v_exp_f32_e32 v71, v71
	v_exp_f32_e32 v72, v72
	v_exp_f32_e32 v73, v73
	v_exp_f32_e32 v74, v74
	v_exp_f32_e32 v75, v75
	v_exp_f32_e32 v76, v76
	v_exp_f32_e32 v77, v77
	v_add_f32_e32 v122, v122, v70
	v_add_f32_e32 v123, v123, v71
	v_add_f32_e32 v122, v122, v72
	v_add_f32_e32 v123, v123, v73
	v_add_f32_e32 v122, v122, v74
	v_add_f32_e32 v123, v123, v75
	v_add_f32_e32 v122, v122, v76
	v_add_f32_e32 v123, v123, v77
	v_cvt_pk_bf16_f32 v238, v70, v71
	v_cvt_pk_bf16_f32 v239, v72, v73
	v_cvt_pk_bf16_f32 v240, v74, v75
	v_cvt_pk_bf16_f32 v241, v76, v77
	v_add_f32_e32 v122, v122, v123
	v_add_f32_e32 v161, v161, v122
	s_waitcnt lgkmcnt(8)
	ds_read_b64_tr_b16 v[222:223], v159 offset:33792
	ds_read_b64_tr_b16 v[224:225], v159 offset:34304
	s_waitcnt vmcnt(0)
	s_waitcnt lgkmcnt(0)
	s_barrier
	v_mfma_f32_32x32x16_bf16 v[14:29], v[190:193], v[226:229], v[14:29]
	v_mfma_f32_32x32x16_bf16 v[30:45], v[194:197], v[226:229], v[30:45]
	v_mfma_f32_32x32x16_bf16 v[14:29], v[198:201], v[230:233], v[14:29]
	v_mfma_f32_32x32x16_bf16 v[30:45], v[202:205], v[230:233], v[30:45]
	v_mfma_f32_32x32x16_bf16 v[14:29], v[206:209], v[234:237], v[14:29]
	v_mfma_f32_32x32x16_bf16 v[30:45], v[210:213], v[234:237], v[30:45]
	v_mfma_f32_32x32x16_bf16 v[14:29], v[214:217], v[238:241], v[14:29]
	v_mfma_f32_32x32x16_bf16 v[30:45], v[222:225], v[238:241], v[30:45]
	v_lshl_add_u64 v[242:243], v[242:243], 0, s[46:47]
	v_lshl_add_u64 v[246:247], v[246:247], 0, s[46:47]

.Lmpro_nokr1:
	s_or_b64 exec, exec, s[10:11]
	v_lshlrev_b32_e32 v15, 4, v34
	v_add_u32_e32 v158, 0, v31
	s_movk_i32 s16, 0xd0
	s_waitcnt vmcnt(2)
	ds_write_b128 v158, v[16:19]
	v_add3_u32 v16, v14, v15, 0
	s_and_saveexec_b64 s[10:11], s[6:7]
	ds_write_b128 v16, v[122:125] offset:128
	s_or_b64 exec, exec, s[10:11]
	v_lshlrev_b32_e32 v17, 12, v23
	v_lshlrev_b32_e32 v18, 6, v30
	v_or3_b32 v17, v15, v17, v18
	v_add_co_u32_e32 v18, vcc, 0x10000, v24
	v_add_u32_e32 v159, 0, v17
	s_nop 0
	v_addc_co_u32_e32 v19, vcc, 0, v25, vcc
	s_waitcnt vmcnt(1)
	ds_write_b128 v159, v[130:133] offset:26624
	s_waitcnt vmcnt(0)
	ds_write_b128 v158, v[126:129] offset:13312
	s_and_saveexec_b64 s[4:5], s[6:7]
	ds_write_b128 v16, v[194:197] offset:13440
	s_or_b64 exec, exec, s[4:5]
	v_lshlrev_b32_e32 v17, 3, v28
	v_lshlrev_b32_e32 v16, 1, v28
	v_and_b32_e32 v17, 24, v17
	v_and_or_b32 v16, v16, 32, v17
	v_lshlrev_b32_e32 v160, 2, v29
	v_lshrrev_b32_e32 v17, 2, v28
	v_and_or_b32 v17, v17, 3, v160
	v_lshl_or_b32 v161, v17, 6, v16
	v_mad_u32_u24 v16, v27, s16, 0
	v_add_u32_e32 v162, v16, v20
	s_waitcnt lgkmcnt(0)
	s_barrier
	ds_read_b128 v[190:193], v162 offset:6656
	ds_read_b128 v[194:197], v162
	ds_read_b128 v[198:201], v162 offset:32
	ds_read_b128 v[202:205], v162 offset:6688
	ds_read_b128 v[206:209], v162 offset:64
	ds_read_b128 v[210:213], v162 offset:6720
	ds_read_b128 v[214:217], v162 offset:96
	ds_read_b128 v[222:225], v162 offset:6752
	ds_read_b128 v[226:229], v162 offset:128
	ds_read_b128 v[230:233], v162 offset:6784
	ds_read_b128 v[16:19], v162 offset:160
	ds_read_b128 v[22:25], v162 offset:6816
	s_waitcnt lgkmcnt(11)
	v_mfma_f32_32x32x16_bf16 v[62:77], v[190:193], v[0:3], 0
	s_add_i32 s35, s35, 4
	s_mov_b32 s52, 0
	s_cmp_eq_u32 s34, 15
	v_add_u32_e32 v163, v14, v15
	v_add_u32_e32 v150, v21, v26
	s_waitcnt lgkmcnt(10)
	v_mfma_f32_32x32x16_bf16 v[46:61], v[194:197], v[0:3], 0
	s_waitcnt lgkmcnt(9)
	v_mfma_f32_32x32x16_bf16 v[46:61], v[198:201], v[4:7], v[46:61]
	s_waitcnt lgkmcnt(8)
	v_mfma_f32_32x32x16_bf16 v[62:77], v[202:205], v[4:7], v[62:77]
	s_waitcnt lgkmcnt(7)
	v_mfma_f32_32x32x16_bf16 v[46:61], v[206:209], v[8:11], v[46:61]
	s_waitcnt lgkmcnt(6)
	v_mfma_f32_32x32x16_bf16 v[62:77], v[210:213], v[8:11], v[62:77]
	s_waitcnt lgkmcnt(5)
	v_mfma_f32_32x32x16_bf16 v[46:61], v[214:217], v[110:113], v[46:61]
	s_waitcnt lgkmcnt(4)
	v_mfma_f32_32x32x16_bf16 v[62:77], v[222:225], v[110:113], v[62:77]
	s_waitcnt lgkmcnt(3)
	v_mfma_f32_32x32x16_bf16 v[46:61], v[226:229], v[114:117], v[46:61]
	s_waitcnt lgkmcnt(2)
	v_mfma_f32_32x32x16_bf16 v[62:77], v[230:233], v[114:117], v[62:77]
	s_waitcnt lgkmcnt(0)
	s_barrier
	v_mfma_f32_32x32x16_bf16 v[46:61], v[16:19], v[118:121], v[46:61]
	v_mfma_f32_32x32x16_bf16 v[62:77], v[22:25], v[118:121], v[62:77]
	v_readfirstlane_b32 s14, v159
	s_add_i32 s15, s14, 0x8800
	s_add_i32 s14, s14, 0x6800
	v_mov_b32_e32 v14, 0
	v_mov_b32_e32 v15, 0
	v_mov_b32_e32 v16, 0
	v_mov_b32_e32 v17, 0
	v_mov_b32_e32 v18, 0
	v_mov_b32_e32 v19, 0
	v_mov_b32_e32 v20, 0
	v_mov_b32_e32 v21, 0
	v_mov_b32_e32 v22, 0
	v_mov_b32_e32 v23, 0
	v_mov_b32_e32 v24, 0
	v_mov_b32_e32 v25, 0
	v_mov_b32_e32 v26, 0
	v_mov_b32_e32 v27, 0
	v_mov_b32_e32 v28, 0
	v_mov_b32_e32 v29, 0
	v_mov_b32_e32 v30, 0
	v_mov_b32_e32 v31, 0
	v_mov_b32_e32 v32, 0
	v_mov_b32_e32 v33, 0
	v_mov_b32_e32 v34, 0
	v_mov_b32_e32 v35, 0
	v_mov_b32_e32 v36, 0
	v_mov_b32_e32 v37, 0
	v_mov_b32_e32 v38, 0
	v_mov_b32_e32 v39, 0
	v_mov_b32_e32 v40, 0
	v_mov_b32_e32 v41, 0
	v_mov_b32_e32 v42, 0
	v_mov_b32_e32 v43, 0
	v_mov_b32_e32 v44, 0
	v_mov_b32_e32 v45, 0
	v_mov_b32_e32 v165, 0
	s_and_b32 s4, s3, 56
	s_lshl_b32 s4, s4, 19
	s_or_b32 s4, s4, s12
	s_add_u32 s54, s22, s4
	s_addc_u32 s55, s23, 0
	s_add_u32 s54, s54, 0x15a20000
	s_addc_u32 s55, s55, 0
	s_add_u32 s56, s22, s96
	s_addc_u32 s57, s23, 0
	s_add_u32 s56, s56, 0x12802000
	s_addc_u32 s57, s57, 0
	v_lshlrev_b32_e32 v226, 1, v148
	v_lshlrev_b32_e32 v227, 1, v12
	v_add_u32_e32 v227, 0x1ff0000, v227
	v_lshlrev_b32_e32 v228, 1, v150
	global_load_dwordx4 v[126:129], v226, s[54:55]
	s_and_saveexec_b64 s[4:5], s[6:7]
	s_cbranch_execz .Lm3_nokrp
	global_load_dwordx4 v[122:125], v228, s[56:57]
.Lm3_nokrp:
	s_or_b64 exec, exec, s[4:5]
	s_mov_b32 m0, s15
	s_nop 0
	global_load_lds_dwordx4 v227, s[54:55]
	s_add_u32 s54, s54, 0x10000
	s_addc_u32 s55, s55, 0
	s_add_u32 s56, s56, 0x1000
	s_addc_u32 s57, s57, 0
	ds_read_b128 v[134:137], v162 offset:13312
	ds_read_b128 v[138:141], v162 offset:19968
	ds_read_b128 v[142:145], v162 offset:13344
	ds_read_b128 v[168:171], v162 offset:20000
	ds_read_b128 v[172:175], v162 offset:13376
	ds_read_b128 v[178:181], v162 offset:20032
	ds_read_b128 v[182:185], v162 offset:13408
	ds_read_b128 v[186:189], v162 offset:20064
	ds_read_b128 v[206:209], v162 offset:13440
	ds_read_b128 v[210:213], v162 offset:20096
	ds_read_b128 v[214:217], v162 offset:13472
	ds_read_b128 v[248:251], v162 offset:20128
	v_max3_f32 v240, v46, v47, v48
	v_max3_f32 v241, v49, v50, v51
	v_max3_f32 v240, v240, v52, v53
	v_max3_f32 v241, v241, v54, v55
	v_max3_f32 v240, v240, v56, v57
	v_max3_f32 v241, v241, v58, v59
	v_max3_f32 v240, v240, v60, v61
	v_max3_f32 v241, v241, v62, v63
	v_max3_f32 v240, v240, v64, v65
	v_max3_f32 v241, v241, v66, v67
	v_max3_f32 v240, v240, v68, v69
	v_max3_f32 v241, v241, v70, v71
	v_max3_f32 v240, v240, v72, v73
	v_max3_f32 v241, v241, v74, v75
	v_max3_f32 v240, v240, v76, v77
	v_max_f32_e32 v240, v240, v241
	v_mov_b32_e32 v241, v240
	s_nop 1
	v_permlane32_swap_b32_e32 v240, v241
	v_max_f32_e32 v244, v240, v241
	v_mov_b32_e32 v164, v244
	v_sub_f32_e32 v190, 0, v244
	v_mov_b32_e32 v191, v190
	v_mov_b32_e32 v192, v190
	v_mov_b32_e32 v193, v190
	v_mov_b32_e32 v194, v190
	v_mov_b32_e32 v195, v190
	v_mov_b32_e32 v196, v190
	v_mov_b32_e32 v197, v190
	v_mov_b32_e32 v198, v190
	v_mov_b32_e32 v199, v190
	v_mov_b32_e32 v200, v190
	v_mov_b32_e32 v201, v190
	v_mov_b32_e32 v202, v190
	v_mov_b32_e32 v203, v190
	v_mov_b32_e32 v204, v190
	v_mov_b32_e32 v205, v190
	v_sub_f32_e32 v46, v46, v164
	v_sub_f32_e32 v47, v47, v164
	v_sub_f32_e32 v48, v48, v164
	v_sub_f32_e32 v49, v49, v164
	v_sub_f32_e32 v50, v50, v164
	v_sub_f32_e32 v51, v51, v164
	v_sub_f32_e32 v52, v52, v164
	v_sub_f32_e32 v53, v53, v164
	v_sub_f32_e32 v54, v54, v164
	v_sub_f32_e32 v55, v55, v164
	v_sub_f32_e32 v56, v56, v164
	v_sub_f32_e32 v57, v57, v164
	v_sub_f32_e32 v58, v58, v164
	v_sub_f32_e32 v59, v59, v164
	v_sub_f32_e32 v60, v60, v164
	v_sub_f32_e32 v61, v61, v164
	v_sub_f32_e32 v62, v62, v164
	v_sub_f32_e32 v63, v63, v164
	v_sub_f32_e32 v64, v64, v164
	v_sub_f32_e32 v65, v65, v164
	v_sub_f32_e32 v66, v66, v164
	v_sub_f32_e32 v67, v67, v164
	v_sub_f32_e32 v68, v68, v164
	v_sub_f32_e32 v69, v69, v164
	v_sub_f32_e32 v70, v70, v164
	v_sub_f32_e32 v71, v71, v164
	v_sub_f32_e32 v72, v72, v164
	v_sub_f32_e32 v73, v73, v164
	v_sub_f32_e32 v74, v74, v164
	v_sub_f32_e32 v75, v75, v164
	v_sub_f32_e32 v76, v76, v164
	v_sub_f32_e32 v77, v77, v164
	v_mov_b32_e32 v244, 0
	s_lshr_b32 s11, s33, 1
	s_mov_b32 s10, 0
	s_cmp_le_u32 s35, 4
	s_cbranch_scc1 .Lm3_tail0

.Lm3_nokwa:
	s_or_b64 exec, exec, s[4:5]
	v_mfma_f32_32x32x16_bf16 v[94:109], v[210:213], v[114:117], v[94:109]
	v_add_f32_e32 v243, v243, v61
	v_exp_f32_e32 v70, v70
	v_exp_f32_e32 v71, v71
	v_exp_f32_e32 v72, v72
	v_mfma_f32_32x32x16_bf16 v[78:93], v[214:217], v[118:121], v[78:93]
	v_exp_f32_e32 v73, v73
	v_exp_f32_e32 v74, v74
	v_exp_f32_e32 v75, v75
	v_exp_f32_e32 v76, v76
	v_mfma_f32_32x32x16_bf16 v[94:109], v[248:251], v[118:121], v[94:109]
	v_exp_f32_e32 v77, v77
	v_add_f32_e32 v238, v238, v62
	v_add_f32_e32 v239, v239, v63
	v_add_f32_e32 v242, v242, v64
	v_add_f32_e32 v243, v243, v65
	s_waitcnt lgkmcnt(0)
	s_barrier
	ds_read_b128 v[206:209], v162 offset:128
	ds_read_b128 v[210:213], v162 offset:6784
	ds_read_b128 v[214:217], v162 offset:160
	ds_read_b128 v[248:251], v162 offset:6816
	v_mfma_f32_32x32x16_bf16 v[14:29], v[134:137], v[152:155], v[14:29]
	ds_read_b128 v[134:137], v162
	v_cvt_pk_bf16_f32 v222, v54, v55
	v_cvt_pk_bf16_f32 v223, v56, v57
	v_cvt_pk_bf16_f32 v224, v58, v59
	v_cvt_pk_bf16_f32 v225, v60, v61
	v_cvt_pk_bf16_f32 v230, v62, v63
	v_cvt_pk_bf16_f32 v231, v64, v65
	v_mfma_f32_32x32x16_bf16 v[30:45], v[138:141], v[152:155], v[30:45]
	ds_read_b128 v[138:141], v162 offset:6656
	global_load_dwordx4 v[126:129], v226, s[54:55]
	s_and_saveexec_b64 s[4:5], s[6:7]
	s_cbranch_execz .Lm3_nokra
	global_load_dwordx4 v[122:125], v228, s[56:57]
.Lm3_nokra:
	s_or_b64 exec, exec, s[4:5]
	v_cvt_pk_bf16_f32 v232, v66, v67
	v_cvt_pk_bf16_f32 v233, v68, v69
	v_add_f32_e32 v238, v238, v66
	v_add_f32_e32 v239, v239, v67
	v_add_f32_e32 v242, v242, v68
	v_add_f32_e32 v243, v243, v69
	v_mfma_f32_32x32x16_bf16 v[14:29], v[142:145], v[222:225], v[14:29]
	ds_read_b128 v[142:145], v162 offset:32
	v_cvt_pk_bf16_f32 v234, v70, v71
	v_cvt_pk_bf16_f32 v235, v72, v73
	v_cvt_pk_bf16_f32 v236, v74, v75
	v_cvt_pk_bf16_f32 v237, v76, v77
	v_add_f32_e32 v238, v238, v70
	v_add_f32_e32 v239, v239, v71
	v_mfma_f32_32x32x16_bf16 v[30:45], v[168:171], v[222:225], v[30:45]
	ds_read_b128 v[168:171], v162 offset:6688
	v_add_f32_e32 v242, v242, v72
	v_add_f32_e32 v243, v243, v73
	v_add_f32_e32 v238, v238, v74
	v_add_f32_e32 v239, v239, v75
	v_add_f32_e32 v242, v242, v76
	v_add_f32_e32 v243, v243, v77
	v_add_f32_e32 v238, v238, v239
	v_mfma_f32_32x32x16_bf16 v[14:29], v[172:175], v[230:233], v[14:29]
	ds_read_b128 v[172:175], v162 offset:64
	v_add_f32_e32 v242, v242, v243
	v_add_f32_e32 v238, v238, v242
	v_add_f32_e32 v165, v165, v238
	v_max3_f32 v240, v78, v79, v80
	v_max3_f32 v241, v81, v82, v83
	v_max3_f32 v240, v240, v84, v85
	v_mfma_f32_32x32x16_bf16 v[30:45], v[178:181], v[230:233], v[30:45]
	ds_read_b128 v[178:181], v162 offset:6720
	s_mov_b32 m0, s14
	s_nop 0
	global_load_lds_dwordx4 v227, s[54:55]
	v_max3_f32 v241, v241, v86, v87
	v_max3_f32 v240, v240, v88, v89
	v_max3_f32 v241, v241, v90, v91
	v_max3_f32 v240, v240, v92, v93
	v_max3_f32 v241, v241, v94, v95
	v_max3_f32 v240, v240, v96, v97
	v_mfma_f32_32x32x16_bf16 v[14:29], v[182:185], v[234:237], v[14:29]
	ds_read_b128 v[182:185], v162 offset:96
	v_max3_f32 v241, v241, v98, v99
	v_max3_f32 v240, v240, v100, v101
	v_max3_f32 v241, v241, v102, v103
	v_max3_f32 v240, v240, v104, v105
	v_max3_f32 v241, v241, v106, v107
	v_mfma_f32_32x32x16_bf16 v[30:45], v[186:189], v[234:237], v[30:45]
	ds_read_b128 v[186:189], v162 offset:6752
	v_max3_f32 v240, v240, v108, v109
	v_max_f32_e32 v240, v240, v241
	v_mov_b32_e32 v241, v240
	s_nop 1
	v_permlane32_swap_b32_e32 v240, v241
	v_max_f32_e32 v244, v240, v241
	s_add_u32 s54, s54, 0x10000
	s_addc_u32 s55, s55, 0
	s_add_u32 s56, s56, 0x1000
	s_addc_u32 s57, s57, 0
	v_cmp_lt_f32_e32 vcc, 0x41800000, v244
	s_cbranch_vccnz .Lm3_rescb

.Lm3_nokwb:
	s_or_b64 exec, exec, s[4:5]
	v_mfma_f32_32x32x16_bf16 v[62:77], v[210:213], v[114:117], v[62:77]
	v_add_f32_e32 v243, v243, v93
	v_exp_f32_e32 v102, v102
	v_exp_f32_e32 v103, v103
	v_exp_f32_e32 v104, v104
	v_mfma_f32_32x32x16_bf16 v[46:61], v[214:217], v[118:121], v[46:61]
	v_exp_f32_e32 v105, v105
	v_exp_f32_e32 v106, v106
	v_exp_f32_e32 v107, v107
	v_exp_f32_e32 v108, v108
	v_mfma_f32_32x32x16_bf16 v[62:77], v[248:251], v[118:121], v[62:77]
	v_exp_f32_e32 v109, v109
	v_add_f32_e32 v238, v238, v94
	v_add_f32_e32 v239, v239, v95
	v_add_f32_e32 v242, v242, v96
	v_add_f32_e32 v243, v243, v97
	s_waitcnt lgkmcnt(0)
	s_barrier
	ds_read_b128 v[206:209], v162 offset:13440
	ds_read_b128 v[210:213], v162 offset:20096
	ds_read_b128 v[214:217], v162 offset:13472
	ds_read_b128 v[248:251], v162 offset:20128
	v_mfma_f32_32x32x16_bf16 v[14:29], v[134:137], v[152:155], v[14:29]
	ds_read_b128 v[134:137], v162 offset:13312
	v_cvt_pk_bf16_f32 v222, v86, v87
	v_cvt_pk_bf16_f32 v223, v88, v89
	v_cvt_pk_bf16_f32 v224, v90, v91
	v_cvt_pk_bf16_f32 v225, v92, v93
	v_cvt_pk_bf16_f32 v230, v94, v95
	v_cvt_pk_bf16_f32 v231, v96, v97
	v_mfma_f32_32x32x16_bf16 v[30:45], v[138:141], v[152:155], v[30:45]
	ds_read_b128 v[138:141], v162 offset:19968
	global_load_dwordx4 v[126:129], v226, s[54:55]
	s_and_saveexec_b64 s[4:5], s[6:7]
	s_cbranch_execz .Lm3_nokrb
	global_load_dwordx4 v[122:125], v228, s[56:57]
.Lm3_nokrb:
	s_or_b64 exec, exec, s[4:5]
	v_cvt_pk_bf16_f32 v232, v98, v99
	v_cvt_pk_bf16_f32 v233, v100, v101
	v_add_f32_e32 v238, v238, v98
	v_add_f32_e32 v239, v239, v99
	v_add_f32_e32 v242, v242, v100
	v_add_f32_e32 v243, v243, v101
	v_mfma_f32_32x32x16_bf16 v[14:29], v[142:145], v[222:225], v[14:29]
	ds_read_b128 v[142:145], v162 offset:13344
	v_cvt_pk_bf16_f32 v234, v102, v103
	v_cvt_pk_bf16_f32 v235, v104, v105
	v_cvt_pk_bf16_f32 v236, v106, v107
	v_cvt_pk_bf16_f32 v237, v108, v109
	v_add_f32_e32 v238, v238, v102
	v_add_f32_e32 v239, v239, v103
	v_mfma_f32_32x32x16_bf16 v[30:45], v[168:171], v[222:225], v[30:45]
	ds_read_b128 v[168:171], v162 offset:20000
	v_add_f32_e32 v242, v242, v104
	v_add_f32_e32 v243, v243, v105
	v_add_f32_e32 v238, v238, v106
	v_add_f32_e32 v239, v239, v107
	v_add_f32_e32 v242, v242, v108
	v_add_f32_e32 v243, v243, v109
	v_add_f32_e32 v238, v238, v239
	v_mfma_f32_32x32x16_bf16 v[14:29], v[172:175], v[230:233], v[14:29]
	ds_read_b128 v[172:175], v162 offset:13376
	v_add_f32_e32 v242, v242, v243
	v_add_f32_e32 v238, v238, v242
	v_add_f32_e32 v165, v165, v238
	v_max3_f32 v240, v46, v47, v48
	v_max3_f32 v241, v49, v50, v51
	v_max3_f32 v240, v240, v52, v53
	v_mfma_f32_32x32x16_bf16 v[30:45], v[178:181], v[230:233], v[30:45]
	ds_read_b128 v[178:181], v162 offset:20032
	s_mov_b32 m0, s15
	s_nop 0
	global_load_lds_dwordx4 v227, s[54:55]
	v_max3_f32 v241, v241, v54, v55
	v_max3_f32 v240, v240, v56, v57
	v_max3_f32 v241, v241, v58, v59
	v_max3_f32 v240, v240, v60, v61
	v_max3_f32 v241, v241, v62, v63
	v_max3_f32 v240, v240, v64, v65
	v_mfma_f32_32x32x16_bf16 v[14:29], v[182:185], v[234:237], v[14:29]
	ds_read_b128 v[182:185], v162 offset:13408
	v_max3_f32 v241, v241, v66, v67
	v_max3_f32 v240, v240, v68, v69
	v_max3_f32 v241, v241, v70, v71
	v_max3_f32 v240, v240, v72, v73
	v_max3_f32 v241, v241, v74, v75
	v_mfma_f32_32x32x16_bf16 v[30:45], v[186:189], v[234:237], v[30:45]
	ds_read_b128 v[186:189], v162 offset:20064
	v_max3_f32 v240, v240, v76, v77
	v_max_f32_e32 v240, v240, v241
	v_mov_b32_e32 v241, v240
	s_nop 1
	v_permlane32_swap_b32_e32 v240, v241
	v_max_f32_e32 v244, v240, v241
	s_add_u32 s54, s54, 0x10000
	s_addc_u32 s55, s55, 0
	s_add_u32 s56, s56, 0x1000
	s_addc_u32 s57, s57, 0
	s_add_i32 s10, s10, 2
	s_add_i32 s4, s10, 4
	s_cmp_lt_u32 s4, s35
	s_cbranch_scc1 .Lm3_loop

.Lm3_nokwt0i:
	s_or_b64 exec, exec, s[4:5]
	s_waitcnt lgkmcnt(0)
	s_barrier
	global_load_dwordx4 v[126:129], v226, s[54:55]
	s_and_saveexec_b64 s[4:5], s[6:7]
	s_cbranch_execz .Lm3_nokrt0i
	global_load_dwordx4 v[122:125], v228, s[56:57]
.Lm3_nokrt0i:
	s_or_b64 exec, exec, s[4:5]
	s_mov_b32 m0, s14
	s_nop 0
	global_load_lds_dwordx4 v227, s[54:55]
	s_add_u32 s54, s54, 0x10000
	s_addc_u32 s55, s55, 0
	s_add_u32 s56, s56, 0x1000
	s_addc_u32 s57, s57, 0
	s_branch .Lm3_tail1

.Lm3_nokwt0l:
	s_or_b64 exec, exec, s[4:5]
	s_waitcnt lgkmcnt(0)
	s_barrier
	v_mfma_f32_32x32x16_bf16 v[14:29], v[134:137], v[152:155], v[14:29]
	v_cvt_pk_bf16_f32 v222, v54, v55
	v_cvt_pk_bf16_f32 v223, v56, v57
	v_cvt_pk_bf16_f32 v224, v58, v59
	v_mfma_f32_32x32x16_bf16 v[30:45], v[138:141], v[152:155], v[30:45]
	global_load_dwordx4 v[126:129], v226, s[54:55]
	s_and_saveexec_b64 s[4:5], s[6:7]
	s_cbranch_execz .Lm3_nokrt0l
	global_load_dwordx4 v[122:125], v228, s[56:57]
.Lm3_nokrt0l:
	s_or_b64 exec, exec, s[4:5]
	v_cvt_pk_bf16_f32 v225, v60, v61
	v_cvt_pk_bf16_f32 v230, v62, v63
	v_cvt_pk_bf16_f32 v231, v64, v65
	v_mfma_f32_32x32x16_bf16 v[14:29], v[142:145], v[222:225], v[14:29]
	v_cvt_pk_bf16_f32 v232, v66, v67
	v_cvt_pk_bf16_f32 v233, v68, v69
	v_add_f32_e32 v238, v238, v66
	v_mfma_f32_32x32x16_bf16 v[30:45], v[168:171], v[222:225], v[30:45]
	v_add_f32_e32 v239, v239, v67
	v_add_f32_e32 v242, v242, v68
	v_add_f32_e32 v243, v243, v69
	v_cvt_pk_bf16_f32 v234, v70, v71
	v_mfma_f32_32x32x16_bf16 v[14:29], v[172:175], v[230:233], v[14:29]
	v_cvt_pk_bf16_f32 v235, v72, v73
	v_cvt_pk_bf16_f32 v236, v74, v75
	v_cvt_pk_bf16_f32 v237, v76, v77
	v_mfma_f32_32x32x16_bf16 v[30:45], v[178:181], v[230:233], v[30:45]
	s_mov_b32 m0, s14
	s_nop 0
	global_load_lds_dwordx4 v227, s[54:55]
	v_add_f32_e32 v238, v238, v70
	v_add_f32_e32 v239, v239, v71
	v_add_f32_e32 v242, v242, v72
	v_add_f32_e32 v243, v243, v73
	v_mfma_f32_32x32x16_bf16 v[14:29], v[182:185], v[234:237], v[14:29]
	v_add_f32_e32 v238, v238, v74
	v_add_f32_e32 v239, v239, v75
	v_add_f32_e32 v242, v242, v76
	v_add_f32_e32 v243, v243, v77
	v_mfma_f32_32x32x16_bf16 v[30:45], v[186:189], v[234:237], v[30:45]
	v_add_f32_e32 v238, v238, v239
	v_add_f32_e32 v242, v242, v243
	v_add_f32_e32 v238, v238, v242
	v_add_f32_e32 v165, v165, v238
	s_add_u32 s54, s54, 0x10000
	s_addc_u32 s55, s55, 0
	s_add_u32 s56, s56, 0x1000
	s_addc_u32 s57, s57, 0
	s_branch .Lm3_tail1

.Lm3_nokrt0f:
	s_or_b64 exec, exec, s[4:5]
	v_cvt_pk_bf16_f32 v232, v66, v67
	v_cvt_pk_bf16_f32 v233, v68, v69
	v_add_f32_e32 v238, v238, v66
	v_add_f32_e32 v239, v239, v67
	v_add_f32_e32 v242, v242, v68
	v_add_f32_e32 v243, v243, v69
	v_mfma_f32_32x32x16_bf16 v[14:29], v[142:145], v[222:225], v[14:29]
	ds_read_b128 v[142:145], v162 offset:32
	v_cvt_pk_bf16_f32 v234, v70, v71
	v_cvt_pk_bf16_f32 v235, v72, v73
	v_cvt_pk_bf16_f32 v236, v74, v75
	v_cvt_pk_bf16_f32 v237, v76, v77
	v_add_f32_e32 v238, v238, v70
	v_add_f32_e32 v239, v239, v71
	v_mfma_f32_32x32x16_bf16 v[30:45], v[168:171], v[222:225], v[30:45]
	ds_read_b128 v[168:171], v162 offset:6688
	v_add_f32_e32 v242, v242, v72
	v_add_f32_e32 v243, v243, v73
	v_add_f32_e32 v238, v238, v74
	v_add_f32_e32 v239, v239, v75
	v_add_f32_e32 v242, v242, v76
	v_add_f32_e32 v243, v243, v77
	v_add_f32_e32 v238, v238, v239
	v_mfma_f32_32x32x16_bf16 v[14:29], v[172:175], v[230:233], v[14:29]
	ds_read_b128 v[172:175], v162 offset:64
	v_add_f32_e32 v242, v242, v243
	v_add_f32_e32 v238, v238, v242
	v_add_f32_e32 v165, v165, v238
	v_max3_f32 v240, v78, v79, v80
	v_max3_f32 v241, v81, v82, v83
	v_max3_f32 v240, v240, v84, v85
	v_mfma_f32_32x32x16_bf16 v[30:45], v[178:181], v[230:233], v[30:45]
	ds_read_b128 v[178:181], v162 offset:6720
	s_mov_b32 m0, s14
	s_nop 0
	global_load_lds_dwordx4 v227, s[54:55]
	v_max3_f32 v241, v241, v86, v87
	v_max3_f32 v240, v240, v88, v89
	v_max3_f32 v241, v241, v90, v91
	v_max3_f32 v240, v240, v92, v93
	v_max3_f32 v241, v241, v94, v95
	v_max3_f32 v240, v240, v96, v97
	v_mfma_f32_32x32x16_bf16 v[14:29], v[182:185], v[234:237], v[14:29]
	ds_read_b128 v[182:185], v162 offset:96
	v_max3_f32 v241, v241, v98, v99
	v_max3_f32 v240, v240, v100, v101
	v_max3_f32 v241, v241, v102, v103
	v_max3_f32 v240, v240, v104, v105
	v_max3_f32 v241, v241, v106, v107
	v_mfma_f32_32x32x16_bf16 v[30:45], v[186:189], v[234:237], v[30:45]
	ds_read_b128 v[186:189], v162 offset:6752
	v_max3_f32 v240, v240, v108, v109
	v_max_f32_e32 v240, v240, v241
	v_mov_b32_e32 v241, v240
	s_nop 1
	v_permlane32_swap_b32_e32 v240, v241
	v_max_f32_e32 v244, v240, v241
	s_add_u32 s54, s54, 0x10000
	s_addc_u32 s55, s55, 0
	s_add_u32 s56, s56, 0x1000
	s_addc_u32 s57, s57, 0

.Lm3_nokwt1i:
	s_or_b64 exec, exec, s[4:5]
	s_waitcnt lgkmcnt(0)
	s_barrier
	s_mov_b32 m0, s15
	s_nop 0
	global_load_lds_dwordx4 v227, s[54:55]
	s_add_u32 s54, s54, 0x10000
	s_addc_u32 s55, s55, 0
	s_add_u32 s56, s56, 0x1000
	s_addc_u32 s57, s57, 0
	s_branch .Lm3_tail2

.Lm3_nokwt1l:
	s_or_b64 exec, exec, s[4:5]
	s_waitcnt lgkmcnt(0)
	s_barrier
	v_mfma_f32_32x32x16_bf16 v[14:29], v[134:137], v[152:155], v[14:29]
	v_cvt_pk_bf16_f32 v222, v86, v87
	v_cvt_pk_bf16_f32 v223, v88, v89
	v_cvt_pk_bf16_f32 v224, v90, v91
	v_mfma_f32_32x32x16_bf16 v[30:45], v[138:141], v[152:155], v[30:45]
	v_cvt_pk_bf16_f32 v225, v92, v93
	v_cvt_pk_bf16_f32 v230, v94, v95
	v_cvt_pk_bf16_f32 v231, v96, v97
	v_mfma_f32_32x32x16_bf16 v[14:29], v[142:145], v[222:225], v[14:29]
	v_cvt_pk_bf16_f32 v232, v98, v99
	v_cvt_pk_bf16_f32 v233, v100, v101
	v_add_f32_e32 v238, v238, v98
	v_mfma_f32_32x32x16_bf16 v[30:45], v[168:171], v[222:225], v[30:45]
	v_add_f32_e32 v239, v239, v99
	v_add_f32_e32 v242, v242, v100
	v_add_f32_e32 v243, v243, v101
	v_cvt_pk_bf16_f32 v234, v102, v103
	v_mfma_f32_32x32x16_bf16 v[14:29], v[172:175], v[230:233], v[14:29]
	v_cvt_pk_bf16_f32 v235, v104, v105
	v_cvt_pk_bf16_f32 v236, v106, v107
	v_cvt_pk_bf16_f32 v237, v108, v109
	v_mfma_f32_32x32x16_bf16 v[30:45], v[178:181], v[230:233], v[30:45]
	s_mov_b32 m0, s15
	s_nop 0
	global_load_lds_dwordx4 v227, s[54:55]
	v_add_f32_e32 v238, v238, v102
	v_add_f32_e32 v239, v239, v103
	v_add_f32_e32 v242, v242, v104
	v_add_f32_e32 v243, v243, v105
	v_mfma_f32_32x32x16_bf16 v[14:29], v[182:185], v[234:237], v[14:29]
	v_add_f32_e32 v238, v238, v106
	v_add_f32_e32 v239, v239, v107
	v_add_f32_e32 v242, v242, v108
	v_add_f32_e32 v243, v243, v109
	v_mfma_f32_32x32x16_bf16 v[30:45], v[186:189], v[234:237], v[30:45]
	v_add_f32_e32 v238, v238, v239
	v_add_f32_e32 v242, v242, v243
	v_add_f32_e32 v238, v238, v242
	v_add_f32_e32 v165, v165, v238
	s_add_u32 s54, s54, 0x10000
	s_addc_u32 s55, s55, 0
	s_add_u32 s56, s56, 0x1000
	s_addc_u32 s57, s57, 0
	s_branch .Lm3_tail2

.Lm3_nokwt1f:
	s_or_b64 exec, exec, s[4:5]
	v_mfma_f32_32x32x16_bf16 v[62:77], v[210:213], v[114:117], v[62:77]
	v_add_f32_e32 v243, v243, v93
	v_exp_f32_e32 v102, v102
	v_exp_f32_e32 v103, v103
	v_exp_f32_e32 v104, v104
	v_mfma_f32_32x32x16_bf16 v[46:61], v[214:217], v[118:121], v[46:61]
	v_exp_f32_e32 v105, v105
	v_exp_f32_e32 v106, v106
	v_exp_f32_e32 v107, v107
	v_exp_f32_e32 v108, v108
	v_mfma_f32_32x32x16_bf16 v[62:77], v[248:251], v[118:121], v[62:77]
	v_exp_f32_e32 v109, v109
	v_add_f32_e32 v238, v238, v94
	v_add_f32_e32 v239, v239, v95
	v_add_f32_e32 v242, v242, v96
	v_add_f32_e32 v243, v243, v97
	s_waitcnt lgkmcnt(0)
	s_barrier
	ds_read_b128 v[206:209], v162 offset:13440
	ds_read_b128 v[210:213], v162 offset:20096
	ds_read_b128 v[214:217], v162 offset:13472
	ds_read_b128 v[248:251], v162 offset:20128
	v_mfma_f32_32x32x16_bf16 v[14:29], v[134:137], v[152:155], v[14:29]
	ds_read_b128 v[134:137], v162 offset:13312
	v_cvt_pk_bf16_f32 v222, v86, v87
	v_cvt_pk_bf16_f32 v223, v88, v89
	v_cvt_pk_bf16_f32 v224, v90, v91
	v_cvt_pk_bf16_f32 v225, v92, v93
	v_cvt_pk_bf16_f32 v230, v94, v95
	v_cvt_pk_bf16_f32 v231, v96, v97
	v_mfma_f32_32x32x16_bf16 v[30:45], v[138:141], v[152:155], v[30:45]
	ds_read_b128 v[138:141], v162 offset:19968
	v_cvt_pk_bf16_f32 v232, v98, v99
	v_cvt_pk_bf16_f32 v233, v100, v101
	v_add_f32_e32 v238, v238, v98
	v_add_f32_e32 v239, v239, v99
	v_add_f32_e32 v242, v242, v100
	v_add_f32_e32 v243, v243, v101
	v_mfma_f32_32x32x16_bf16 v[14:29], v[142:145], v[222:225], v[14:29]
	ds_read_b128 v[142:145], v162 offset:13344
	v_cvt_pk_bf16_f32 v234, v102, v103
	v_cvt_pk_bf16_f32 v235, v104, v105
	v_cvt_pk_bf16_f32 v236, v106, v107
	v_cvt_pk_bf16_f32 v237, v108, v109
	v_add_f32_e32 v238, v238, v102
	v_add_f32_e32 v239, v239, v103
	v_mfma_f32_32x32x16_bf16 v[30:45], v[168:171], v[222:225], v[30:45]
	ds_read_b128 v[168:171], v162 offset:20000
	v_add_f32_e32 v242, v242, v104
	v_add_f32_e32 v243, v243, v105
	v_add_f32_e32 v238, v238, v106
	v_add_f32_e32 v239, v239, v107
	v_add_f32_e32 v242, v242, v108
	v_add_f32_e32 v243, v243, v109
	v_add_f32_e32 v238, v238, v239
	v_mfma_f32_32x32x16_bf16 v[14:29], v[172:175], v[230:233], v[14:29]
	ds_read_b128 v[172:175], v162 offset:13376
	v_add_f32_e32 v242, v242, v243
	v_add_f32_e32 v238, v238, v242
	v_add_f32_e32 v165, v165, v238
	v_max3_f32 v240, v46, v47, v48
	v_max3_f32 v241, v49, v50, v51
	v_max3_f32 v240, v240, v52, v53
	v_mfma_f32_32x32x16_bf16 v[30:45], v[178:181], v[230:233], v[30:45]
	ds_read_b128 v[178:181], v162 offset:20032
	s_mov_b32 m0, s15
	s_nop 0
	global_load_lds_dwordx4 v227, s[54:55]
	v_max3_f32 v241, v241, v54, v55
	v_max3_f32 v240, v240, v56, v57
	v_max3_f32 v241, v241, v58, v59
	v_max3_f32 v240, v240, v60, v61
	v_max3_f32 v241, v241, v62, v63
	v_max3_f32 v240, v240, v64, v65
	v_mfma_f32_32x32x16_bf16 v[14:29], v[182:185], v[234:237], v[14:29]
	ds_read_b128 v[182:185], v162 offset:13408
	v_max3_f32 v241, v241, v66, v67
	v_max3_f32 v240, v240, v68, v69
	v_max3_f32 v241, v241, v70, v71
	v_max3_f32 v240, v240, v72, v73
	v_max3_f32 v241, v241, v74, v75
	v_mfma_f32_32x32x16_bf16 v[30:45], v[186:189], v[234:237], v[30:45]
	ds_read_b128 v[186:189], v162 offset:20064
	v_max3_f32 v240, v240, v76, v77
	v_max_f32_e32 v240, v240, v241
	v_mov_b32_e32 v241, v240
	s_nop 1
	v_permlane32_swap_b32_e32 v240, v241
	v_max_f32_e32 v244, v240, v241
	s_add_u32 s54, s54, 0x10000
	s_addc_u32 s55, s55, 0
	s_add_u32 s56, s56, 0x1000
	s_addc_u32 s57, s57, 0
.Lm3_tail2:
	s_cmp_gt_u32 s11, 2
	s_cbranch_scc1 .Lm3_t2_full
	s_cmp_eq_u32 s11, 2
	s_cbranch_scc1 .Lm3_t2_last
	s_waitcnt lgkmcnt(0)
	s_waitcnt vmcnt(0)
	s_waitcnt lgkmcnt(0)
	s_barrier
	s_add_u32 s54, s54, 0x10000
	s_addc_u32 s55, s55, 0
	s_add_u32 s56, s56, 0x1000
	s_addc_u32 s57, s57, 0
	s_branch .Lm3_tail3

.Lm3_resc_rett2l:
	s_waitcnt lgkmcnt(0)
	ds_read_b64_tr_b16 v[134:135], v161 offset:26624
	ds_read_b64_tr_b16 v[136:137], v161 offset:27136
	ds_read_b64_tr_b16 v[138:139], v161 offset:30720
	ds_read_b64_tr_b16 v[140:141], v161 offset:31232
	ds_read_b64_tr_b16 v[142:143], v161 offset:27648
	ds_read_b64_tr_b16 v[144:145], v161 offset:28160
	ds_read_b64_tr_b16 v[168:169], v161 offset:31744
	ds_read_b64_tr_b16 v[170:171], v161 offset:32256
	ds_read_b64_tr_b16 v[172:173], v161 offset:28672
	ds_read_b64_tr_b16 v[174:175], v161 offset:29184
	ds_read_b64_tr_b16 v[178:179], v161 offset:32768
	ds_read_b64_tr_b16 v[180:181], v161 offset:33280
	ds_read_b64_tr_b16 v[182:183], v161 offset:29696
	ds_read_b64_tr_b16 v[184:185], v161 offset:30208
	v_exp_f32_e32 v46, v46
	v_exp_f32_e32 v47, v47
	v_exp_f32_e32 v48, v48
	v_exp_f32_e32 v49, v49
	v_exp_f32_e32 v50, v50
	v_exp_f32_e32 v51, v51
	v_exp_f32_e32 v52, v52
	v_exp_f32_e32 v53, v53
	v_cvt_pk_bf16_f32 v152, v46, v47
	v_cvt_pk_bf16_f32 v153, v48, v49
	v_cvt_pk_bf16_f32 v154, v50, v51
	v_cvt_pk_bf16_f32 v155, v52, v53
	v_exp_f32_e32 v54, v54
	v_exp_f32_e32 v55, v55
	v_exp_f32_e32 v56, v56
	v_exp_f32_e32 v57, v57
	v_exp_f32_e32 v58, v58
	v_exp_f32_e32 v59, v59
	v_exp_f32_e32 v60, v60
	v_exp_f32_e32 v61, v61
	v_add_f32_e32 v238, v46, v47
	v_add_f32_e32 v239, v48, v49
	v_add_f32_e32 v242, v50, v51
	v_add_f32_e32 v243, v52, v53
	v_exp_f32_e32 v62, v62
	v_exp_f32_e32 v63, v63
	v_exp_f32_e32 v64, v64
	v_exp_f32_e32 v65, v65
	v_exp_f32_e32 v66, v66
	v_exp_f32_e32 v67, v67
	v_exp_f32_e32 v68, v68
	v_exp_f32_e32 v69, v69
	v_add_f32_e32 v238, v238, v54
	v_add_f32_e32 v239, v239, v55
	v_add_f32_e32 v242, v242, v56
	v_add_f32_e32 v243, v243, v57
	v_add_f32_e32 v238, v238, v58
	v_add_f32_e32 v239, v239, v59
	v_add_f32_e32 v242, v242, v60
	v_add_f32_e32 v243, v243, v61
	v_exp_f32_e32 v70, v70
	v_exp_f32_e32 v71, v71
	v_exp_f32_e32 v72, v72
	v_exp_f32_e32 v73, v73
	v_exp_f32_e32 v74, v74
	v_exp_f32_e32 v75, v75
	v_exp_f32_e32 v76, v76
	v_exp_f32_e32 v77, v77
	v_add_f32_e32 v238, v238, v62
	v_add_f32_e32 v239, v239, v63
	v_add_f32_e32 v242, v242, v64
	v_add_f32_e32 v243, v243, v65
	s_waitcnt lgkmcnt(8)
	ds_read_b64_tr_b16 v[186:187], v161 offset:33792
	ds_read_b64_tr_b16 v[188:189], v161 offset:34304
	s_waitcnt vmcnt(0)
	s_waitcnt lgkmcnt(0)
	s_barrier
	v_mfma_f32_32x32x16_bf16 v[14:29], v[134:137], v[152:155], v[14:29]
	v_cvt_pk_bf16_f32 v222, v54, v55
	v_cvt_pk_bf16_f32 v223, v56, v57
	v_cvt_pk_bf16_f32 v224, v58, v59
	v_mfma_f32_32x32x16_bf16 v[30:45], v[138:141], v[152:155], v[30:45]
	v_cvt_pk_bf16_f32 v225, v60, v61
	v_cvt_pk_bf16_f32 v230, v62, v63
	v_cvt_pk_bf16_f32 v231, v64, v65
	v_mfma_f32_32x32x16_bf16 v[14:29], v[142:145], v[222:225], v[14:29]
	v_cvt_pk_bf16_f32 v232, v66, v67
	v_cvt_pk_bf16_f32 v233, v68, v69
	v_add_f32_e32 v238, v238, v66
	v_mfma_f32_32x32x16_bf16 v[30:45], v[168:171], v[222:225], v[30:45]
	v_add_f32_e32 v239, v239, v67
	v_add_f32_e32 v242, v242, v68
	v_add_f32_e32 v243, v243, v69
	v_cvt_pk_bf16_f32 v234, v70, v71
	v_mfma_f32_32x32x16_bf16 v[14:29], v[172:175], v[230:233], v[14:29]
	v_cvt_pk_bf16_f32 v235, v72, v73
	v_cvt_pk_bf16_f32 v236, v74, v75
	v_cvt_pk_bf16_f32 v237, v76, v77
	v_mfma_f32_32x32x16_bf16 v[30:45], v[178:181], v[230:233], v[30:45]
	v_add_f32_e32 v238, v238, v70
	v_add_f32_e32 v239, v239, v71
	v_add_f32_e32 v242, v242, v72
	v_add_f32_e32 v243, v243, v73
	v_mfma_f32_32x32x16_bf16 v[14:29], v[182:185], v[234:237], v[14:29]
	v_add_f32_e32 v238, v238, v74
	v_add_f32_e32 v239, v239, v75
	v_add_f32_e32 v242, v242, v76
	v_add_f32_e32 v243, v243, v77
	v_mfma_f32_32x32x16_bf16 v[30:45], v[186:189], v[234:237], v[30:45]
	v_add_f32_e32 v238, v238, v239
	v_add_f32_e32 v242, v242, v243
	v_add_f32_e32 v238, v238, v242
	v_add_f32_e32 v165, v165, v238
	s_add_u32 s54, s54, 0x10000
	s_addc_u32 s55, s55, 0
	s_add_u32 s56, s56, 0x1000
	s_addc_u32 s57, s57, 0
	s_branch .Lm3_tail3

.Lm3_resc_rett2f:
	s_waitcnt lgkmcnt(7)
	v_mfma_f32_32x32x16_bf16 v[78:93], v[134:137], v[0:3], v[190:205]
	ds_read_b64_tr_b16 v[134:135], v161 offset:26624
	ds_read_b64_tr_b16 v[136:137], v161 offset:27136
	v_exp_f32_e32 v46, v46
	v_exp_f32_e32 v47, v47
	v_exp_f32_e32 v48, v48
	v_exp_f32_e32 v49, v49
	s_waitcnt lgkmcnt(8)
	v_mfma_f32_32x32x16_bf16 v[94:109], v[138:141], v[0:3], v[190:205]
	ds_read_b64_tr_b16 v[138:139], v161 offset:30720
	ds_read_b64_tr_b16 v[140:141], v161 offset:31232
	v_exp_f32_e32 v50, v50
	v_exp_f32_e32 v51, v51
	v_exp_f32_e32 v52, v52
	v_exp_f32_e32 v53, v53
	s_waitcnt lgkmcnt(9)
	v_mfma_f32_32x32x16_bf16 v[78:93], v[142:145], v[4:7], v[78:93]
	ds_read_b64_tr_b16 v[142:143], v161 offset:27648
	ds_read_b64_tr_b16 v[144:145], v161 offset:28160
	v_cvt_pk_bf16_f32 v152, v46, v47
	v_cvt_pk_bf16_f32 v153, v48, v49
	v_cvt_pk_bf16_f32 v154, v50, v51
	v_cvt_pk_bf16_f32 v155, v52, v53
	s_waitcnt lgkmcnt(10)
	v_mfma_f32_32x32x16_bf16 v[94:109], v[168:171], v[4:7], v[94:109]
	ds_read_b64_tr_b16 v[168:169], v161 offset:31744
	ds_read_b64_tr_b16 v[170:171], v161 offset:32256
	v_exp_f32_e32 v54, v54
	v_exp_f32_e32 v55, v55
	v_exp_f32_e32 v56, v56
	v_exp_f32_e32 v57, v57
	s_waitcnt lgkmcnt(11)
	v_mfma_f32_32x32x16_bf16 v[78:93], v[172:175], v[8:11], v[78:93]
	ds_read_b64_tr_b16 v[172:173], v161 offset:28672
	ds_read_b64_tr_b16 v[174:175], v161 offset:29184
	v_exp_f32_e32 v58, v58
	v_exp_f32_e32 v59, v59
	v_exp_f32_e32 v60, v60
	s_waitcnt lgkmcnt(12)
	v_mfma_f32_32x32x16_bf16 v[94:109], v[178:181], v[8:11], v[94:109]
	ds_read_b64_tr_b16 v[178:179], v161 offset:32768
	ds_read_b64_tr_b16 v[180:181], v161 offset:33280
	v_exp_f32_e32 v61, v61
	v_add_f32_e32 v238, v46, v47
	v_add_f32_e32 v239, v48, v49
	v_add_f32_e32 v242, v50, v51
	v_add_f32_e32 v243, v52, v53
	v_exp_f32_e32 v62, v62
	s_waitcnt lgkmcnt(13)
	v_mfma_f32_32x32x16_bf16 v[78:93], v[182:185], v[110:113], v[78:93]
	ds_read_b64_tr_b16 v[182:183], v161 offset:29696
	ds_read_b64_tr_b16 v[184:185], v161 offset:30208
	v_exp_f32_e32 v63, v63
	v_exp_f32_e32 v64, v64
	v_exp_f32_e32 v65, v65
	v_exp_f32_e32 v66, v66
	s_waitcnt lgkmcnt(14)
	v_mfma_f32_32x32x16_bf16 v[94:109], v[186:189], v[110:113], v[94:109]
	s_waitcnt lgkmcnt(13)
	ds_read_b64_tr_b16 v[186:187], v161 offset:33792
	ds_read_b64_tr_b16 v[188:189], v161 offset:34304
	v_exp_f32_e32 v67, v67
	v_exp_f32_e32 v68, v68
	v_exp_f32_e32 v69, v69
	v_mfma_f32_32x32x16_bf16 v[78:93], v[206:209], v[114:117], v[78:93]
	v_add_f32_e32 v238, v238, v54
	v_add_f32_e32 v239, v239, v55
	v_add_f32_e32 v242, v242, v56
	v_add_f32_e32 v243, v243, v57
	v_add_f32_e32 v238, v238, v58
	v_add_f32_e32 v239, v239, v59
	v_add_f32_e32 v242, v242, v60
	s_waitcnt lgkmcnt(8)
	s_waitcnt vmcnt(0)
	v_mfma_f32_32x32x16_bf16 v[94:109], v[210:213], v[114:117], v[94:109]
	v_add_f32_e32 v243, v243, v61
	v_exp_f32_e32 v70, v70
	v_exp_f32_e32 v71, v71
	v_exp_f32_e32 v72, v72
	v_mfma_f32_32x32x16_bf16 v[78:93], v[214:217], v[118:121], v[78:93]
	v_exp_f32_e32 v73, v73
	v_exp_f32_e32 v74, v74
	v_exp_f32_e32 v75, v75
	v_exp_f32_e32 v76, v76
	v_mfma_f32_32x32x16_bf16 v[94:109], v[248:251], v[118:121], v[94:109]
	v_exp_f32_e32 v77, v77
	v_add_f32_e32 v238, v238, v62
	v_add_f32_e32 v239, v239, v63
	v_add_f32_e32 v242, v242, v64
	v_add_f32_e32 v243, v243, v65
	s_waitcnt lgkmcnt(0)
	s_barrier
	ds_read_b128 v[206:209], v162 offset:128
	ds_read_b128 v[210:213], v162 offset:6784
	ds_read_b128 v[214:217], v162 offset:160
	ds_read_b128 v[248:251], v162 offset:6816
	v_mfma_f32_32x32x16_bf16 v[14:29], v[134:137], v[152:155], v[14:29]
	ds_read_b128 v[134:137], v162
	v_cvt_pk_bf16_f32 v222, v54, v55
	v_cvt_pk_bf16_f32 v223, v56, v57
	v_cvt_pk_bf16_f32 v224, v58, v59
	v_cvt_pk_bf16_f32 v225, v60, v61
	v_cvt_pk_bf16_f32 v230, v62, v63
	v_cvt_pk_bf16_f32 v231, v64, v65
	v_mfma_f32_32x32x16_bf16 v[30:45], v[138:141], v[152:155], v[30:45]
	ds_read_b128 v[138:141], v162 offset:6656
	v_cvt_pk_bf16_f32 v232, v66, v67
	v_cvt_pk_bf16_f32 v233, v68, v69
	v_add_f32_e32 v238, v238, v66
	v_add_f32_e32 v239, v239, v67
	v_add_f32_e32 v242, v242, v68
	v_add_f32_e32 v243, v243, v69
	v_mfma_f32_32x32x16_bf16 v[14:29], v[142:145], v[222:225], v[14:29]
	ds_read_b128 v[142:145], v162 offset:32
	v_cvt_pk_bf16_f32 v234, v70, v71
	v_cvt_pk_bf16_f32 v235, v72, v73
	v_cvt_pk_bf16_f32 v236, v74, v75
	v_cvt_pk_bf16_f32 v237, v76, v77
	v_add_f32_e32 v238, v238, v70
	v_add_f32_e32 v239, v239, v71
	v_mfma_f32_32x32x16_bf16 v[30:45], v[168:171], v[222:225], v[30:45]
	ds_read_b128 v[168:171], v162 offset:6688
	v_add_f32_e32 v242, v242, v72
	v_add_f32_e32 v243, v243, v73
	v_add_f32_e32 v238, v238, v74
	v_add_f32_e32 v239, v239, v75
	v_add_f32_e32 v242, v242, v76
	v_add_f32_e32 v243, v243, v77
	v_add_f32_e32 v238, v238, v239
	v_mfma_f32_32x32x16_bf16 v[14:29], v[172:175], v[230:233], v[14:29]
	ds_read_b128 v[172:175], v162 offset:64
	v_add_f32_e32 v242, v242, v243
	v_add_f32_e32 v238, v238, v242
	v_add_f32_e32 v165, v165, v238
	v_max3_f32 v240, v78, v79, v80
	v_max3_f32 v241, v81, v82, v83
	v_max3_f32 v240, v240, v84, v85
	v_mfma_f32_32x32x16_bf16 v[30:45], v[178:181], v[230:233], v[30:45]
	ds_read_b128 v[178:181], v162 offset:6720
	v_max3_f32 v241, v241, v86, v87
	v_max3_f32 v240, v240, v88, v89
	v_max3_f32 v241, v241, v90, v91
	v_max3_f32 v240, v240, v92, v93
	v_max3_f32 v241, v241, v94, v95
	v_max3_f32 v240, v240, v96, v97
	v_mfma_f32_32x32x16_bf16 v[14:29], v[182:185], v[234:237], v[14:29]
	ds_read_b128 v[182:185], v162 offset:96
	v_max3_f32 v241, v241, v98, v99
	v_max3_f32 v240, v240, v100, v101
	v_max3_f32 v241, v241, v102, v103
	v_max3_f32 v240, v240, v104, v105
	v_max3_f32 v241, v241, v106, v107
	v_mfma_f32_32x32x16_bf16 v[30:45], v[186:189], v[234:237], v[30:45]
	ds_read_b128 v[186:189], v162 offset:6752
	v_max3_f32 v240, v240, v108, v109
	v_max_f32_e32 v240, v240, v241
	v_mov_b32_e32 v241, v240
	s_nop 1
	v_permlane32_swap_b32_e32 v240, v241
	v_max_f32_e32 v244, v240, v241
	s_add_u32 s54, s54, 0x10000
	s_addc_u32 s55, s55, 0
	s_add_u32 s56, s56, 0x1000
	s_addc_u32 s57, s57, 0
